# FoX: K-norm pre-pass (Kmax^2 per b,h) + Cauchy-Schwarz bound: wave stops when all older keys are provably below mref-152, workgroup leaves the tile loop when all 8 waves are stopped
# speedup vs baseline: 1.0018x; 1.0018x over previous
.Lq_init:
	s_add_u32 s90, s54, 0x80000
	s_addc_u32 s91, s55, 0
	s_lshr_b32 s95, s88, 2
	s_and_b32 s96, s88, 3
	s_lshr_b32 s97, s95, 4
	s_and_b32 s89, s95, 15
	s_lshl_b32 s97, s97, 12
	s_lshl_b32 s96, s96, 10
	s_add_i32 s97, s97, s96
	s_lshl_b32 s97, s97, 14
	s_lshl_b32 s89, s89, 8
	s_add_i32 s97, s97, s89
	s_addk_i32 s97, 0x1000
	s_add_u32 s96, s12, s97
	s_addc_u32 s97, s13, 0
	s_lshl_b32 s95, s95, 2
	s_addk_i32 s95, 640
	v_lshrrev_b32_e32 v2, 4, v255
	v_lshlrev_b32_e32 v2, 14, v2
	v_and_b32_e32 v3, 15, v255
	v_lshl_add_u32 v2, v3, 4, v2
	global_load_dwordx4 v[4:7], v2, s[96:97]
	v_add_u32_e32 v2, 0x80000, v2
	global_load_dwordx4 v[8:11], v2, s[96:97]
	v_add_u32_e32 v2, 0x80000, v2
	global_load_dwordx4 v[12:15], v2, s[96:97]
	v_add_u32_e32 v2, 0x80000, v2
	global_load_dwordx4 v[16:19], v2, s[96:97]
	v_add_u32_e32 v2, 0x80000, v2
	global_load_dwordx4 v[20:23], v2, s[96:97]
	v_add_u32_e32 v2, 0x80000, v2
	global_load_dwordx4 v[24:27], v2, s[96:97]
	v_add_u32_e32 v2, 0x80000, v2
	global_load_dwordx4 v[28:31], v2, s[96:97]
	v_add_u32_e32 v2, 0x80000, v2
	global_load_dwordx4 v[32:35], v2, s[96:97]
	v_add_u32_e32 v2, 0x80000, v2
	global_load_dwordx4 v[36:39], v2, s[96:97]
	v_add_u32_e32 v2, 0x80000, v2
	global_load_dwordx4 v[40:43], v2, s[96:97]
	v_add_u32_e32 v2, 0x80000, v2
	global_load_dwordx4 v[44:47], v2, s[96:97]
	v_add_u32_e32 v2, 0x80000, v2
	global_load_dwordx4 v[48:51], v2, s[96:97]
	v_add_u32_e32 v2, 0x80000, v2
	global_load_dwordx4 v[52:55], v2, s[96:97]
	v_add_u32_e32 v2, 0x80000, v2
	global_load_dwordx4 v[56:59], v2, s[96:97]
	v_add_u32_e32 v2, 0x80000, v2
	global_load_dwordx4 v[60:63], v2, s[96:97]
	v_add_u32_e32 v2, 0x80000, v2
	global_load_dwordx4 v[64:67], v2, s[96:97]
	v_add_u32_e32 v2, 0x80000, v2
	global_load_dwordx4 v[68:71], v2, s[96:97]
	v_add_u32_e32 v2, 0x80000, v2
	global_load_dwordx4 v[72:75], v2, s[96:97]
	v_add_u32_e32 v2, 0x80000, v2
	global_load_dwordx4 v[76:79], v2, s[96:97]
	v_add_u32_e32 v2, 0x80000, v2
	global_load_dwordx4 v[80:83], v2, s[96:97]
	v_add_u32_e32 v2, 0x80000, v2
	global_load_dwordx4 v[84:87], v2, s[96:97]
	v_add_u32_e32 v2, 0x80000, v2
	global_load_dwordx4 v[88:91], v2, s[96:97]
	v_add_u32_e32 v2, 0x80000, v2
	global_load_dwordx4 v[92:95], v2, s[96:97]
	v_add_u32_e32 v2, 0x80000, v2
	global_load_dwordx4 v[96:99], v2, s[96:97]
	v_add_u32_e32 v2, 0x80000, v2
	global_load_dwordx4 v[100:103], v2, s[96:97]
	v_add_u32_e32 v2, 0x80000, v2
	global_load_dwordx4 v[104:107], v2, s[96:97]
	v_add_u32_e32 v2, 0x80000, v2
	global_load_dwordx4 v[108:111], v2, s[96:97]
	v_add_u32_e32 v2, 0x80000, v2
	global_load_dwordx4 v[112:115], v2, s[96:97]
	v_add_u32_e32 v2, 0x80000, v2
	global_load_dwordx4 v[116:119], v2, s[96:97]
	v_add_u32_e32 v2, 0x80000, v2
	global_load_dwordx4 v[120:123], v2, s[96:97]
	v_add_u32_e32 v2, 0x80000, v2
	global_load_dwordx4 v[124:127], v2, s[96:97]
	v_add_u32_e32 v2, 0x80000, v2
	global_load_dwordx4 v[128:131], v2, s[96:97]
	v_mov_b32_e32 v135, 0
	s_waitcnt vmcnt(31)
	v_lshlrev_b32_e32 v133, 16, v4
	v_and_b32_e32 v134, 0xffff0000, v4
	v_mul_f32_e32 v132, v133, v133
	v_fmac_f32_e32 v132, v134, v134
	v_lshlrev_b32_e32 v133, 16, v5
	v_and_b32_e32 v134, 0xffff0000, v5
	v_fmac_f32_e32 v132, v133, v133
	v_fmac_f32_e32 v132, v134, v134
	v_lshlrev_b32_e32 v133, 16, v6
	v_and_b32_e32 v134, 0xffff0000, v6
	v_fmac_f32_e32 v132, v133, v133
	v_fmac_f32_e32 v132, v134, v134
	v_lshlrev_b32_e32 v133, 16, v7
	v_and_b32_e32 v134, 0xffff0000, v7
	v_fmac_f32_e32 v132, v133, v133
	v_fmac_f32_e32 v132, v134, v134
	s_nop 1
	v_add_f32_dpp v132, v132, v132 row_ror:8 row_mask:0xf bank_mask:0xf
	s_nop 1
	v_add_f32_dpp v132, v132, v132 row_ror:4 row_mask:0xf bank_mask:0xf
	s_nop 1
	v_add_f32_dpp v132, v132, v132 row_ror:2 row_mask:0xf bank_mask:0xf
	s_nop 1
	v_add_f32_dpp v132, v132, v132 row_ror:1 row_mask:0xf bank_mask:0xf
	v_max_f32_e32 v135, v135, v132
	s_waitcnt vmcnt(30)
	v_lshlrev_b32_e32 v133, 16, v8
	v_and_b32_e32 v134, 0xffff0000, v8
	v_mul_f32_e32 v132, v133, v133
	v_fmac_f32_e32 v132, v134, v134
	v_lshlrev_b32_e32 v133, 16, v9
	v_and_b32_e32 v134, 0xffff0000, v9
	v_fmac_f32_e32 v132, v133, v133
	v_fmac_f32_e32 v132, v134, v134
	v_lshlrev_b32_e32 v133, 16, v10
	v_and_b32_e32 v134, 0xffff0000, v10
	v_fmac_f32_e32 v132, v133, v133
	v_fmac_f32_e32 v132, v134, v134
	v_lshlrev_b32_e32 v133, 16, v11
	v_and_b32_e32 v134, 0xffff0000, v11
	v_fmac_f32_e32 v132, v133, v133
	v_fmac_f32_e32 v132, v134, v134
	s_nop 1
	v_add_f32_dpp v132, v132, v132 row_ror:8 row_mask:0xf bank_mask:0xf
	s_nop 1
	v_add_f32_dpp v132, v132, v132 row_ror:4 row_mask:0xf bank_mask:0xf
	s_nop 1
	v_add_f32_dpp v132, v132, v132 row_ror:2 row_mask:0xf bank_mask:0xf
	s_nop 1
	v_add_f32_dpp v132, v132, v132 row_ror:1 row_mask:0xf bank_mask:0xf
	v_max_f32_e32 v135, v135, v132
	s_waitcnt vmcnt(29)
	v_lshlrev_b32_e32 v133, 16, v12
	v_and_b32_e32 v134, 0xffff0000, v12
	v_mul_f32_e32 v132, v133, v133
	v_fmac_f32_e32 v132, v134, v134
	v_lshlrev_b32_e32 v133, 16, v13
	v_and_b32_e32 v134, 0xffff0000, v13
	v_fmac_f32_e32 v132, v133, v133
	v_fmac_f32_e32 v132, v134, v134
	v_lshlrev_b32_e32 v133, 16, v14
	v_and_b32_e32 v134, 0xffff0000, v14
	v_fmac_f32_e32 v132, v133, v133
	v_fmac_f32_e32 v132, v134, v134
	v_lshlrev_b32_e32 v133, 16, v15
	v_and_b32_e32 v134, 0xffff0000, v15
	v_fmac_f32_e32 v132, v133, v133
	v_fmac_f32_e32 v132, v134, v134
	s_nop 1
	v_add_f32_dpp v132, v132, v132 row_ror:8 row_mask:0xf bank_mask:0xf
	s_nop 1
	v_add_f32_dpp v132, v132, v132 row_ror:4 row_mask:0xf bank_mask:0xf
	s_nop 1
	v_add_f32_dpp v132, v132, v132 row_ror:2 row_mask:0xf bank_mask:0xf
	s_nop 1
	v_add_f32_dpp v132, v132, v132 row_ror:1 row_mask:0xf bank_mask:0xf
	v_max_f32_e32 v135, v135, v132
	s_waitcnt vmcnt(28)
	v_lshlrev_b32_e32 v133, 16, v16
	v_and_b32_e32 v134, 0xffff0000, v16
	v_mul_f32_e32 v132, v133, v133
	v_fmac_f32_e32 v132, v134, v134
	v_lshlrev_b32_e32 v133, 16, v17
	v_and_b32_e32 v134, 0xffff0000, v17
	v_fmac_f32_e32 v132, v133, v133
	v_fmac_f32_e32 v132, v134, v134
	v_lshlrev_b32_e32 v133, 16, v18
	v_and_b32_e32 v134, 0xffff0000, v18
	v_fmac_f32_e32 v132, v133, v133
	v_fmac_f32_e32 v132, v134, v134
	v_lshlrev_b32_e32 v133, 16, v19
	v_and_b32_e32 v134, 0xffff0000, v19
	v_fmac_f32_e32 v132, v133, v133
	v_fmac_f32_e32 v132, v134, v134
	s_nop 1
	v_add_f32_dpp v132, v132, v132 row_ror:8 row_mask:0xf bank_mask:0xf
	s_nop 1
	v_add_f32_dpp v132, v132, v132 row_ror:4 row_mask:0xf bank_mask:0xf
	s_nop 1
	v_add_f32_dpp v132, v132, v132 row_ror:2 row_mask:0xf bank_mask:0xf
	s_nop 1
	v_add_f32_dpp v132, v132, v132 row_ror:1 row_mask:0xf bank_mask:0xf
	v_max_f32_e32 v135, v135, v132
	s_waitcnt vmcnt(27)
	v_lshlrev_b32_e32 v133, 16, v20
	v_and_b32_e32 v134, 0xffff0000, v20
	v_mul_f32_e32 v132, v133, v133
	v_fmac_f32_e32 v132, v134, v134
	v_lshlrev_b32_e32 v133, 16, v21
	v_and_b32_e32 v134, 0xffff0000, v21
	v_fmac_f32_e32 v132, v133, v133
	v_fmac_f32_e32 v132, v134, v134
	v_lshlrev_b32_e32 v133, 16, v22
	v_and_b32_e32 v134, 0xffff0000, v22
	v_fmac_f32_e32 v132, v133, v133
	v_fmac_f32_e32 v132, v134, v134
	v_lshlrev_b32_e32 v133, 16, v23
	v_and_b32_e32 v134, 0xffff0000, v23
	v_fmac_f32_e32 v132, v133, v133
	v_fmac_f32_e32 v132, v134, v134
	s_nop 1
	v_add_f32_dpp v132, v132, v132 row_ror:8 row_mask:0xf bank_mask:0xf
	s_nop 1
	v_add_f32_dpp v132, v132, v132 row_ror:4 row_mask:0xf bank_mask:0xf
	s_nop 1
	v_add_f32_dpp v132, v132, v132 row_ror:2 row_mask:0xf bank_mask:0xf
	s_nop 1
	v_add_f32_dpp v132, v132, v132 row_ror:1 row_mask:0xf bank_mask:0xf
	v_max_f32_e32 v135, v135, v132
	s_waitcnt vmcnt(26)
	v_lshlrev_b32_e32 v133, 16, v24
	v_and_b32_e32 v134, 0xffff0000, v24
	v_mul_f32_e32 v132, v133, v133
	v_fmac_f32_e32 v132, v134, v134
	v_lshlrev_b32_e32 v133, 16, v25
	v_and_b32_e32 v134, 0xffff0000, v25
	v_fmac_f32_e32 v132, v133, v133
	v_fmac_f32_e32 v132, v134, v134
	v_lshlrev_b32_e32 v133, 16, v26
	v_and_b32_e32 v134, 0xffff0000, v26
	v_fmac_f32_e32 v132, v133, v133
	v_fmac_f32_e32 v132, v134, v134
	v_lshlrev_b32_e32 v133, 16, v27
	v_and_b32_e32 v134, 0xffff0000, v27
	v_fmac_f32_e32 v132, v133, v133
	v_fmac_f32_e32 v132, v134, v134
	s_nop 1
	v_add_f32_dpp v132, v132, v132 row_ror:8 row_mask:0xf bank_mask:0xf
	s_nop 1
	v_add_f32_dpp v132, v132, v132 row_ror:4 row_mask:0xf bank_mask:0xf
	s_nop 1
	v_add_f32_dpp v132, v132, v132 row_ror:2 row_mask:0xf bank_mask:0xf
	s_nop 1
	v_add_f32_dpp v132, v132, v132 row_ror:1 row_mask:0xf bank_mask:0xf
	v_max_f32_e32 v135, v135, v132
	s_waitcnt vmcnt(25)
	v_lshlrev_b32_e32 v133, 16, v28
	v_and_b32_e32 v134, 0xffff0000, v28
	v_mul_f32_e32 v132, v133, v133
	v_fmac_f32_e32 v132, v134, v134
	v_lshlrev_b32_e32 v133, 16, v29
	v_and_b32_e32 v134, 0xffff0000, v29
	v_fmac_f32_e32 v132, v133, v133
	v_fmac_f32_e32 v132, v134, v134
	v_lshlrev_b32_e32 v133, 16, v30
	v_and_b32_e32 v134, 0xffff0000, v30
	v_fmac_f32_e32 v132, v133, v133
	v_fmac_f32_e32 v132, v134, v134
	v_lshlrev_b32_e32 v133, 16, v31
	v_and_b32_e32 v134, 0xffff0000, v31
	v_fmac_f32_e32 v132, v133, v133
	v_fmac_f32_e32 v132, v134, v134
	s_nop 1
	v_add_f32_dpp v132, v132, v132 row_ror:8 row_mask:0xf bank_mask:0xf
	s_nop 1
	v_add_f32_dpp v132, v132, v132 row_ror:4 row_mask:0xf bank_mask:0xf
	s_nop 1
	v_add_f32_dpp v132, v132, v132 row_ror:2 row_mask:0xf bank_mask:0xf
	s_nop 1
	v_add_f32_dpp v132, v132, v132 row_ror:1 row_mask:0xf bank_mask:0xf
	v_max_f32_e32 v135, v135, v132
	s_waitcnt vmcnt(24)
	v_lshlrev_b32_e32 v133, 16, v32
	v_and_b32_e32 v134, 0xffff0000, v32
	v_mul_f32_e32 v132, v133, v133
	v_fmac_f32_e32 v132, v134, v134
	v_lshlrev_b32_e32 v133, 16, v33
	v_and_b32_e32 v134, 0xffff0000, v33
	v_fmac_f32_e32 v132, v133, v133
	v_fmac_f32_e32 v132, v134, v134
	v_lshlrev_b32_e32 v133, 16, v34
	v_and_b32_e32 v134, 0xffff0000, v34
	v_fmac_f32_e32 v132, v133, v133
	v_fmac_f32_e32 v132, v134, v134
	v_lshlrev_b32_e32 v133, 16, v35
	v_and_b32_e32 v134, 0xffff0000, v35
	v_fmac_f32_e32 v132, v133, v133
	v_fmac_f32_e32 v132, v134, v134
	s_nop 1
	v_add_f32_dpp v132, v132, v132 row_ror:8 row_mask:0xf bank_mask:0xf
	s_nop 1
	v_add_f32_dpp v132, v132, v132 row_ror:4 row_mask:0xf bank_mask:0xf
	s_nop 1
	v_add_f32_dpp v132, v132, v132 row_ror:2 row_mask:0xf bank_mask:0xf
	s_nop 1
	v_add_f32_dpp v132, v132, v132 row_ror:1 row_mask:0xf bank_mask:0xf
	v_max_f32_e32 v135, v135, v132
	s_waitcnt vmcnt(23)
	v_lshlrev_b32_e32 v133, 16, v36
	v_and_b32_e32 v134, 0xffff0000, v36
	v_mul_f32_e32 v132, v133, v133
	v_fmac_f32_e32 v132, v134, v134
	v_lshlrev_b32_e32 v133, 16, v37
	v_and_b32_e32 v134, 0xffff0000, v37
	v_fmac_f32_e32 v132, v133, v133
	v_fmac_f32_e32 v132, v134, v134
	v_lshlrev_b32_e32 v133, 16, v38
	v_and_b32_e32 v134, 0xffff0000, v38
	v_fmac_f32_e32 v132, v133, v133
	v_fmac_f32_e32 v132, v134, v134
	v_lshlrev_b32_e32 v133, 16, v39
	v_and_b32_e32 v134, 0xffff0000, v39
	v_fmac_f32_e32 v132, v133, v133
	v_fmac_f32_e32 v132, v134, v134
	s_nop 1
	v_add_f32_dpp v132, v132, v132 row_ror:8 row_mask:0xf bank_mask:0xf
	s_nop 1
	v_add_f32_dpp v132, v132, v132 row_ror:4 row_mask:0xf bank_mask:0xf
	s_nop 1
	v_add_f32_dpp v132, v132, v132 row_ror:2 row_mask:0xf bank_mask:0xf
	s_nop 1
	v_add_f32_dpp v132, v132, v132 row_ror:1 row_mask:0xf bank_mask:0xf
	v_max_f32_e32 v135, v135, v132
	s_waitcnt vmcnt(22)
	v_lshlrev_b32_e32 v133, 16, v40
	v_and_b32_e32 v134, 0xffff0000, v40
	v_mul_f32_e32 v132, v133, v133
	v_fmac_f32_e32 v132, v134, v134
	v_lshlrev_b32_e32 v133, 16, v41
	v_and_b32_e32 v134, 0xffff0000, v41
	v_fmac_f32_e32 v132, v133, v133
	v_fmac_f32_e32 v132, v134, v134
	v_lshlrev_b32_e32 v133, 16, v42
	v_and_b32_e32 v134, 0xffff0000, v42
	v_fmac_f32_e32 v132, v133, v133
	v_fmac_f32_e32 v132, v134, v134
	v_lshlrev_b32_e32 v133, 16, v43
	v_and_b32_e32 v134, 0xffff0000, v43
	v_fmac_f32_e32 v132, v133, v133
	v_fmac_f32_e32 v132, v134, v134
	s_nop 1
	v_add_f32_dpp v132, v132, v132 row_ror:8 row_mask:0xf bank_mask:0xf
	s_nop 1
	v_add_f32_dpp v132, v132, v132 row_ror:4 row_mask:0xf bank_mask:0xf
	s_nop 1
	v_add_f32_dpp v132, v132, v132 row_ror:2 row_mask:0xf bank_mask:0xf
	s_nop 1
	v_add_f32_dpp v132, v132, v132 row_ror:1 row_mask:0xf bank_mask:0xf
	v_max_f32_e32 v135, v135, v132
	s_waitcnt vmcnt(21)
	v_lshlrev_b32_e32 v133, 16, v44
	v_and_b32_e32 v134, 0xffff0000, v44
	v_mul_f32_e32 v132, v133, v133
	v_fmac_f32_e32 v132, v134, v134
	v_lshlrev_b32_e32 v133, 16, v45
	v_and_b32_e32 v134, 0xffff0000, v45
	v_fmac_f32_e32 v132, v133, v133
	v_fmac_f32_e32 v132, v134, v134
	v_lshlrev_b32_e32 v133, 16, v46
	v_and_b32_e32 v134, 0xffff0000, v46
	v_fmac_f32_e32 v132, v133, v133
	v_fmac_f32_e32 v132, v134, v134
	v_lshlrev_b32_e32 v133, 16, v47
	v_and_b32_e32 v134, 0xffff0000, v47
	v_fmac_f32_e32 v132, v133, v133
	v_fmac_f32_e32 v132, v134, v134
	s_nop 1
	v_add_f32_dpp v132, v132, v132 row_ror:8 row_mask:0xf bank_mask:0xf
	s_nop 1
	v_add_f32_dpp v132, v132, v132 row_ror:4 row_mask:0xf bank_mask:0xf
	s_nop 1
	v_add_f32_dpp v132, v132, v132 row_ror:2 row_mask:0xf bank_mask:0xf
	s_nop 1
	v_add_f32_dpp v132, v132, v132 row_ror:1 row_mask:0xf bank_mask:0xf
	v_max_f32_e32 v135, v135, v132
	s_waitcnt vmcnt(20)
	v_lshlrev_b32_e32 v133, 16, v48
	v_and_b32_e32 v134, 0xffff0000, v48
	v_mul_f32_e32 v132, v133, v133
	v_fmac_f32_e32 v132, v134, v134
	v_lshlrev_b32_e32 v133, 16, v49
	v_and_b32_e32 v134, 0xffff0000, v49
	v_fmac_f32_e32 v132, v133, v133
	v_fmac_f32_e32 v132, v134, v134
	v_lshlrev_b32_e32 v133, 16, v50
	v_and_b32_e32 v134, 0xffff0000, v50
	v_fmac_f32_e32 v132, v133, v133
	v_fmac_f32_e32 v132, v134, v134
	v_lshlrev_b32_e32 v133, 16, v51
	v_and_b32_e32 v134, 0xffff0000, v51
	v_fmac_f32_e32 v132, v133, v133
	v_fmac_f32_e32 v132, v134, v134
	s_nop 1
	v_add_f32_dpp v132, v132, v132 row_ror:8 row_mask:0xf bank_mask:0xf
	s_nop 1
	v_add_f32_dpp v132, v132, v132 row_ror:4 row_mask:0xf bank_mask:0xf
	s_nop 1
	v_add_f32_dpp v132, v132, v132 row_ror:2 row_mask:0xf bank_mask:0xf
	s_nop 1
	v_add_f32_dpp v132, v132, v132 row_ror:1 row_mask:0xf bank_mask:0xf
	v_max_f32_e32 v135, v135, v132
	s_waitcnt vmcnt(19)
	v_lshlrev_b32_e32 v133, 16, v52
	v_and_b32_e32 v134, 0xffff0000, v52
	v_mul_f32_e32 v132, v133, v133
	v_fmac_f32_e32 v132, v134, v134
	v_lshlrev_b32_e32 v133, 16, v53
	v_and_b32_e32 v134, 0xffff0000, v53
	v_fmac_f32_e32 v132, v133, v133
	v_fmac_f32_e32 v132, v134, v134
	v_lshlrev_b32_e32 v133, 16, v54
	v_and_b32_e32 v134, 0xffff0000, v54
	v_fmac_f32_e32 v132, v133, v133
	v_fmac_f32_e32 v132, v134, v134
	v_lshlrev_b32_e32 v133, 16, v55
	v_and_b32_e32 v134, 0xffff0000, v55
	v_fmac_f32_e32 v132, v133, v133
	v_fmac_f32_e32 v132, v134, v134
	s_nop 1
	v_add_f32_dpp v132, v132, v132 row_ror:8 row_mask:0xf bank_mask:0xf
	s_nop 1
	v_add_f32_dpp v132, v132, v132 row_ror:4 row_mask:0xf bank_mask:0xf
	s_nop 1
	v_add_f32_dpp v132, v132, v132 row_ror:2 row_mask:0xf bank_mask:0xf
	s_nop 1
	v_add_f32_dpp v132, v132, v132 row_ror:1 row_mask:0xf bank_mask:0xf
	v_max_f32_e32 v135, v135, v132
	s_waitcnt vmcnt(18)
	v_lshlrev_b32_e32 v133, 16, v56
	v_and_b32_e32 v134, 0xffff0000, v56
	v_mul_f32_e32 v132, v133, v133
	v_fmac_f32_e32 v132, v134, v134
	v_lshlrev_b32_e32 v133, 16, v57
	v_and_b32_e32 v134, 0xffff0000, v57
	v_fmac_f32_e32 v132, v133, v133
	v_fmac_f32_e32 v132, v134, v134
	v_lshlrev_b32_e32 v133, 16, v58
	v_and_b32_e32 v134, 0xffff0000, v58
	v_fmac_f32_e32 v132, v133, v133
	v_fmac_f32_e32 v132, v134, v134
	v_lshlrev_b32_e32 v133, 16, v59
	v_and_b32_e32 v134, 0xffff0000, v59
	v_fmac_f32_e32 v132, v133, v133
	v_fmac_f32_e32 v132, v134, v134
	s_nop 1
	v_add_f32_dpp v132, v132, v132 row_ror:8 row_mask:0xf bank_mask:0xf
	s_nop 1
	v_add_f32_dpp v132, v132, v132 row_ror:4 row_mask:0xf bank_mask:0xf
	s_nop 1
	v_add_f32_dpp v132, v132, v132 row_ror:2 row_mask:0xf bank_mask:0xf
	s_nop 1
	v_add_f32_dpp v132, v132, v132 row_ror:1 row_mask:0xf bank_mask:0xf
	v_max_f32_e32 v135, v135, v132
	s_waitcnt vmcnt(17)
	v_lshlrev_b32_e32 v133, 16, v60
	v_and_b32_e32 v134, 0xffff0000, v60
	v_mul_f32_e32 v132, v133, v133
	v_fmac_f32_e32 v132, v134, v134
	v_lshlrev_b32_e32 v133, 16, v61
	v_and_b32_e32 v134, 0xffff0000, v61
	v_fmac_f32_e32 v132, v133, v133
	v_fmac_f32_e32 v132, v134, v134
	v_lshlrev_b32_e32 v133, 16, v62
	v_and_b32_e32 v134, 0xffff0000, v62
	v_fmac_f32_e32 v132, v133, v133
	v_fmac_f32_e32 v132, v134, v134
	v_lshlrev_b32_e32 v133, 16, v63
	v_and_b32_e32 v134, 0xffff0000, v63
	v_fmac_f32_e32 v132, v133, v133
	v_fmac_f32_e32 v132, v134, v134
	s_nop 1
	v_add_f32_dpp v132, v132, v132 row_ror:8 row_mask:0xf bank_mask:0xf
	s_nop 1
	v_add_f32_dpp v132, v132, v132 row_ror:4 row_mask:0xf bank_mask:0xf
	s_nop 1
	v_add_f32_dpp v132, v132, v132 row_ror:2 row_mask:0xf bank_mask:0xf
	s_nop 1
	v_add_f32_dpp v132, v132, v132 row_ror:1 row_mask:0xf bank_mask:0xf
	v_max_f32_e32 v135, v135, v132
	s_waitcnt vmcnt(16)
	v_lshlrev_b32_e32 v133, 16, v64
	v_and_b32_e32 v134, 0xffff0000, v64
	v_mul_f32_e32 v132, v133, v133
	v_fmac_f32_e32 v132, v134, v134
	v_lshlrev_b32_e32 v133, 16, v65
	v_and_b32_e32 v134, 0xffff0000, v65
	v_fmac_f32_e32 v132, v133, v133
	v_fmac_f32_e32 v132, v134, v134
	v_lshlrev_b32_e32 v133, 16, v66
	v_and_b32_e32 v134, 0xffff0000, v66
	v_fmac_f32_e32 v132, v133, v133
	v_fmac_f32_e32 v132, v134, v134
	v_lshlrev_b32_e32 v133, 16, v67
	v_and_b32_e32 v134, 0xffff0000, v67
	v_fmac_f32_e32 v132, v133, v133
	v_fmac_f32_e32 v132, v134, v134
	s_nop 1
	v_add_f32_dpp v132, v132, v132 row_ror:8 row_mask:0xf bank_mask:0xf
	s_nop 1
	v_add_f32_dpp v132, v132, v132 row_ror:4 row_mask:0xf bank_mask:0xf
	s_nop 1
	v_add_f32_dpp v132, v132, v132 row_ror:2 row_mask:0xf bank_mask:0xf
	s_nop 1
	v_add_f32_dpp v132, v132, v132 row_ror:1 row_mask:0xf bank_mask:0xf
	v_max_f32_e32 v135, v135, v132
	s_waitcnt vmcnt(15)
	v_lshlrev_b32_e32 v133, 16, v68
	v_and_b32_e32 v134, 0xffff0000, v68
	v_mul_f32_e32 v132, v133, v133
	v_fmac_f32_e32 v132, v134, v134
	v_lshlrev_b32_e32 v133, 16, v69
	v_and_b32_e32 v134, 0xffff0000, v69
	v_fmac_f32_e32 v132, v133, v133
	v_fmac_f32_e32 v132, v134, v134
	v_lshlrev_b32_e32 v133, 16, v70
	v_and_b32_e32 v134, 0xffff0000, v70
	v_fmac_f32_e32 v132, v133, v133
	v_fmac_f32_e32 v132, v134, v134
	v_lshlrev_b32_e32 v133, 16, v71
	v_and_b32_e32 v134, 0xffff0000, v71
	v_fmac_f32_e32 v132, v133, v133
	v_fmac_f32_e32 v132, v134, v134
	s_nop 1
	v_add_f32_dpp v132, v132, v132 row_ror:8 row_mask:0xf bank_mask:0xf
	s_nop 1
	v_add_f32_dpp v132, v132, v132 row_ror:4 row_mask:0xf bank_mask:0xf
	s_nop 1
	v_add_f32_dpp v132, v132, v132 row_ror:2 row_mask:0xf bank_mask:0xf
	s_nop 1
	v_add_f32_dpp v132, v132, v132 row_ror:1 row_mask:0xf bank_mask:0xf
	v_max_f32_e32 v135, v135, v132
	s_waitcnt vmcnt(14)
	v_lshlrev_b32_e32 v133, 16, v72
	v_and_b32_e32 v134, 0xffff0000, v72
	v_mul_f32_e32 v132, v133, v133
	v_fmac_f32_e32 v132, v134, v134
	v_lshlrev_b32_e32 v133, 16, v73
	v_and_b32_e32 v134, 0xffff0000, v73
	v_fmac_f32_e32 v132, v133, v133
	v_fmac_f32_e32 v132, v134, v134
	v_lshlrev_b32_e32 v133, 16, v74
	v_and_b32_e32 v134, 0xffff0000, v74
	v_fmac_f32_e32 v132, v133, v133
	v_fmac_f32_e32 v132, v134, v134
	v_lshlrev_b32_e32 v133, 16, v75
	v_and_b32_e32 v134, 0xffff0000, v75
	v_fmac_f32_e32 v132, v133, v133
	v_fmac_f32_e32 v132, v134, v134
	s_nop 1
	v_add_f32_dpp v132, v132, v132 row_ror:8 row_mask:0xf bank_mask:0xf
	s_nop 1
	v_add_f32_dpp v132, v132, v132 row_ror:4 row_mask:0xf bank_mask:0xf
	s_nop 1
	v_add_f32_dpp v132, v132, v132 row_ror:2 row_mask:0xf bank_mask:0xf
	s_nop 1
	v_add_f32_dpp v132, v132, v132 row_ror:1 row_mask:0xf bank_mask:0xf
	v_max_f32_e32 v135, v135, v132
	s_waitcnt vmcnt(13)
	v_lshlrev_b32_e32 v133, 16, v76
	v_and_b32_e32 v134, 0xffff0000, v76
	v_mul_f32_e32 v132, v133, v133
	v_fmac_f32_e32 v132, v134, v134
	v_lshlrev_b32_e32 v133, 16, v77
	v_and_b32_e32 v134, 0xffff0000, v77
	v_fmac_f32_e32 v132, v133, v133
	v_fmac_f32_e32 v132, v134, v134
	v_lshlrev_b32_e32 v133, 16, v78
	v_and_b32_e32 v134, 0xffff0000, v78
	v_fmac_f32_e32 v132, v133, v133
	v_fmac_f32_e32 v132, v134, v134
	v_lshlrev_b32_e32 v133, 16, v79
	v_and_b32_e32 v134, 0xffff0000, v79
	v_fmac_f32_e32 v132, v133, v133
	v_fmac_f32_e32 v132, v134, v134
	s_nop 1
	v_add_f32_dpp v132, v132, v132 row_ror:8 row_mask:0xf bank_mask:0xf
	s_nop 1
	v_add_f32_dpp v132, v132, v132 row_ror:4 row_mask:0xf bank_mask:0xf
	s_nop 1
	v_add_f32_dpp v132, v132, v132 row_ror:2 row_mask:0xf bank_mask:0xf
	s_nop 1
	v_add_f32_dpp v132, v132, v132 row_ror:1 row_mask:0xf bank_mask:0xf
	v_max_f32_e32 v135, v135, v132
	s_waitcnt vmcnt(12)
	v_lshlrev_b32_e32 v133, 16, v80
	v_and_b32_e32 v134, 0xffff0000, v80
	v_mul_f32_e32 v132, v133, v133
	v_fmac_f32_e32 v132, v134, v134
	v_lshlrev_b32_e32 v133, 16, v81
	v_and_b32_e32 v134, 0xffff0000, v81
	v_fmac_f32_e32 v132, v133, v133
	v_fmac_f32_e32 v132, v134, v134
	v_lshlrev_b32_e32 v133, 16, v82
	v_and_b32_e32 v134, 0xffff0000, v82
	v_fmac_f32_e32 v132, v133, v133
	v_fmac_f32_e32 v132, v134, v134
	v_lshlrev_b32_e32 v133, 16, v83
	v_and_b32_e32 v134, 0xffff0000, v83
	v_fmac_f32_e32 v132, v133, v133
	v_fmac_f32_e32 v132, v134, v134
	s_nop 1
	v_add_f32_dpp v132, v132, v132 row_ror:8 row_mask:0xf bank_mask:0xf
	s_nop 1
	v_add_f32_dpp v132, v132, v132 row_ror:4 row_mask:0xf bank_mask:0xf
	s_nop 1
	v_add_f32_dpp v132, v132, v132 row_ror:2 row_mask:0xf bank_mask:0xf
	s_nop 1
	v_add_f32_dpp v132, v132, v132 row_ror:1 row_mask:0xf bank_mask:0xf
	v_max_f32_e32 v135, v135, v132
	s_waitcnt vmcnt(11)
	v_lshlrev_b32_e32 v133, 16, v84
	v_and_b32_e32 v134, 0xffff0000, v84
	v_mul_f32_e32 v132, v133, v133
	v_fmac_f32_e32 v132, v134, v134
	v_lshlrev_b32_e32 v133, 16, v85
	v_and_b32_e32 v134, 0xffff0000, v85
	v_fmac_f32_e32 v132, v133, v133
	v_fmac_f32_e32 v132, v134, v134
	v_lshlrev_b32_e32 v133, 16, v86
	v_and_b32_e32 v134, 0xffff0000, v86
	v_fmac_f32_e32 v132, v133, v133
	v_fmac_f32_e32 v132, v134, v134
	v_lshlrev_b32_e32 v133, 16, v87
	v_and_b32_e32 v134, 0xffff0000, v87
	v_fmac_f32_e32 v132, v133, v133
	v_fmac_f32_e32 v132, v134, v134
	s_nop 1
	v_add_f32_dpp v132, v132, v132 row_ror:8 row_mask:0xf bank_mask:0xf
	s_nop 1
	v_add_f32_dpp v132, v132, v132 row_ror:4 row_mask:0xf bank_mask:0xf
	s_nop 1
	v_add_f32_dpp v132, v132, v132 row_ror:2 row_mask:0xf bank_mask:0xf
	s_nop 1
	v_add_f32_dpp v132, v132, v132 row_ror:1 row_mask:0xf bank_mask:0xf
	v_max_f32_e32 v135, v135, v132
	s_waitcnt vmcnt(10)
	v_lshlrev_b32_e32 v133, 16, v88
	v_and_b32_e32 v134, 0xffff0000, v88
	v_mul_f32_e32 v132, v133, v133
	v_fmac_f32_e32 v132, v134, v134
	v_lshlrev_b32_e32 v133, 16, v89
	v_and_b32_e32 v134, 0xffff0000, v89
	v_fmac_f32_e32 v132, v133, v133
	v_fmac_f32_e32 v132, v134, v134
	v_lshlrev_b32_e32 v133, 16, v90
	v_and_b32_e32 v134, 0xffff0000, v90
	v_fmac_f32_e32 v132, v133, v133
	v_fmac_f32_e32 v132, v134, v134
	v_lshlrev_b32_e32 v133, 16, v91
	v_and_b32_e32 v134, 0xffff0000, v91
	v_fmac_f32_e32 v132, v133, v133
	v_fmac_f32_e32 v132, v134, v134
	s_nop 1
	v_add_f32_dpp v132, v132, v132 row_ror:8 row_mask:0xf bank_mask:0xf
	s_nop 1
	v_add_f32_dpp v132, v132, v132 row_ror:4 row_mask:0xf bank_mask:0xf
	s_nop 1
	v_add_f32_dpp v132, v132, v132 row_ror:2 row_mask:0xf bank_mask:0xf
	s_nop 1
	v_add_f32_dpp v132, v132, v132 row_ror:1 row_mask:0xf bank_mask:0xf
	v_max_f32_e32 v135, v135, v132
	s_waitcnt vmcnt(9)
	v_lshlrev_b32_e32 v133, 16, v92
	v_and_b32_e32 v134, 0xffff0000, v92
	v_mul_f32_e32 v132, v133, v133
	v_fmac_f32_e32 v132, v134, v134
	v_lshlrev_b32_e32 v133, 16, v93
	v_and_b32_e32 v134, 0xffff0000, v93
	v_fmac_f32_e32 v132, v133, v133
	v_fmac_f32_e32 v132, v134, v134
	v_lshlrev_b32_e32 v133, 16, v94
	v_and_b32_e32 v134, 0xffff0000, v94
	v_fmac_f32_e32 v132, v133, v133
	v_fmac_f32_e32 v132, v134, v134
	v_lshlrev_b32_e32 v133, 16, v95
	v_and_b32_e32 v134, 0xffff0000, v95
	v_fmac_f32_e32 v132, v133, v133
	v_fmac_f32_e32 v132, v134, v134
	s_nop 1
	v_add_f32_dpp v132, v132, v132 row_ror:8 row_mask:0xf bank_mask:0xf
	s_nop 1
	v_add_f32_dpp v132, v132, v132 row_ror:4 row_mask:0xf bank_mask:0xf
	s_nop 1
	v_add_f32_dpp v132, v132, v132 row_ror:2 row_mask:0xf bank_mask:0xf
	s_nop 1
	v_add_f32_dpp v132, v132, v132 row_ror:1 row_mask:0xf bank_mask:0xf
	v_max_f32_e32 v135, v135, v132
	s_waitcnt vmcnt(8)
	v_lshlrev_b32_e32 v133, 16, v96
	v_and_b32_e32 v134, 0xffff0000, v96
	v_mul_f32_e32 v132, v133, v133
	v_fmac_f32_e32 v132, v134, v134
	v_lshlrev_b32_e32 v133, 16, v97
	v_and_b32_e32 v134, 0xffff0000, v97
	v_fmac_f32_e32 v132, v133, v133
	v_fmac_f32_e32 v132, v134, v134
	v_lshlrev_b32_e32 v133, 16, v98
	v_and_b32_e32 v134, 0xffff0000, v98
	v_fmac_f32_e32 v132, v133, v133
	v_fmac_f32_e32 v132, v134, v134
	v_lshlrev_b32_e32 v133, 16, v99
	v_and_b32_e32 v134, 0xffff0000, v99
	v_fmac_f32_e32 v132, v133, v133
	v_fmac_f32_e32 v132, v134, v134
	s_nop 1
	v_add_f32_dpp v132, v132, v132 row_ror:8 row_mask:0xf bank_mask:0xf
	s_nop 1
	v_add_f32_dpp v132, v132, v132 row_ror:4 row_mask:0xf bank_mask:0xf
	s_nop 1
	v_add_f32_dpp v132, v132, v132 row_ror:2 row_mask:0xf bank_mask:0xf
	s_nop 1
	v_add_f32_dpp v132, v132, v132 row_ror:1 row_mask:0xf bank_mask:0xf
	v_max_f32_e32 v135, v135, v132
	s_waitcnt vmcnt(7)
	v_lshlrev_b32_e32 v133, 16, v100
	v_and_b32_e32 v134, 0xffff0000, v100
	v_mul_f32_e32 v132, v133, v133
	v_fmac_f32_e32 v132, v134, v134
	v_lshlrev_b32_e32 v133, 16, v101
	v_and_b32_e32 v134, 0xffff0000, v101
	v_fmac_f32_e32 v132, v133, v133
	v_fmac_f32_e32 v132, v134, v134
	v_lshlrev_b32_e32 v133, 16, v102
	v_and_b32_e32 v134, 0xffff0000, v102
	v_fmac_f32_e32 v132, v133, v133
	v_fmac_f32_e32 v132, v134, v134
	v_lshlrev_b32_e32 v133, 16, v103
	v_and_b32_e32 v134, 0xffff0000, v103
	v_fmac_f32_e32 v132, v133, v133
	v_fmac_f32_e32 v132, v134, v134
	s_nop 1
	v_add_f32_dpp v132, v132, v132 row_ror:8 row_mask:0xf bank_mask:0xf
	s_nop 1
	v_add_f32_dpp v132, v132, v132 row_ror:4 row_mask:0xf bank_mask:0xf
	s_nop 1
	v_add_f32_dpp v132, v132, v132 row_ror:2 row_mask:0xf bank_mask:0xf
	s_nop 1
	v_add_f32_dpp v132, v132, v132 row_ror:1 row_mask:0xf bank_mask:0xf
	v_max_f32_e32 v135, v135, v132
	s_waitcnt vmcnt(6)
	v_lshlrev_b32_e32 v133, 16, v104
	v_and_b32_e32 v134, 0xffff0000, v104
	v_mul_f32_e32 v132, v133, v133
	v_fmac_f32_e32 v132, v134, v134
	v_lshlrev_b32_e32 v133, 16, v105
	v_and_b32_e32 v134, 0xffff0000, v105
	v_fmac_f32_e32 v132, v133, v133
	v_fmac_f32_e32 v132, v134, v134
	v_lshlrev_b32_e32 v133, 16, v106
	v_and_b32_e32 v134, 0xffff0000, v106
	v_fmac_f32_e32 v132, v133, v133
	v_fmac_f32_e32 v132, v134, v134
	v_lshlrev_b32_e32 v133, 16, v107
	v_and_b32_e32 v134, 0xffff0000, v107
	v_fmac_f32_e32 v132, v133, v133
	v_fmac_f32_e32 v132, v134, v134
	s_nop 1
	v_add_f32_dpp v132, v132, v132 row_ror:8 row_mask:0xf bank_mask:0xf
	s_nop 1
	v_add_f32_dpp v132, v132, v132 row_ror:4 row_mask:0xf bank_mask:0xf
	s_nop 1
	v_add_f32_dpp v132, v132, v132 row_ror:2 row_mask:0xf bank_mask:0xf
	s_nop 1
	v_add_f32_dpp v132, v132, v132 row_ror:1 row_mask:0xf bank_mask:0xf
	v_max_f32_e32 v135, v135, v132
	s_waitcnt vmcnt(5)
	v_lshlrev_b32_e32 v133, 16, v108
	v_and_b32_e32 v134, 0xffff0000, v108
	v_mul_f32_e32 v132, v133, v133
	v_fmac_f32_e32 v132, v134, v134
	v_lshlrev_b32_e32 v133, 16, v109
	v_and_b32_e32 v134, 0xffff0000, v109
	v_fmac_f32_e32 v132, v133, v133
	v_fmac_f32_e32 v132, v134, v134
	v_lshlrev_b32_e32 v133, 16, v110
	v_and_b32_e32 v134, 0xffff0000, v110
	v_fmac_f32_e32 v132, v133, v133
	v_fmac_f32_e32 v132, v134, v134
	v_lshlrev_b32_e32 v133, 16, v111
	v_and_b32_e32 v134, 0xffff0000, v111
	v_fmac_f32_e32 v132, v133, v133
	v_fmac_f32_e32 v132, v134, v134
	s_nop 1
	v_add_f32_dpp v132, v132, v132 row_ror:8 row_mask:0xf bank_mask:0xf
	s_nop 1
	v_add_f32_dpp v132, v132, v132 row_ror:4 row_mask:0xf bank_mask:0xf
	s_nop 1
	v_add_f32_dpp v132, v132, v132 row_ror:2 row_mask:0xf bank_mask:0xf
	s_nop 1
	v_add_f32_dpp v132, v132, v132 row_ror:1 row_mask:0xf bank_mask:0xf
	v_max_f32_e32 v135, v135, v132
	s_waitcnt vmcnt(4)
	v_lshlrev_b32_e32 v133, 16, v112
	v_and_b32_e32 v134, 0xffff0000, v112
	v_mul_f32_e32 v132, v133, v133
	v_fmac_f32_e32 v132, v134, v134
	v_lshlrev_b32_e32 v133, 16, v113
	v_and_b32_e32 v134, 0xffff0000, v113
	v_fmac_f32_e32 v132, v133, v133
	v_fmac_f32_e32 v132, v134, v134
	v_lshlrev_b32_e32 v133, 16, v114
	v_and_b32_e32 v134, 0xffff0000, v114
	v_fmac_f32_e32 v132, v133, v133
	v_fmac_f32_e32 v132, v134, v134
	v_lshlrev_b32_e32 v133, 16, v115
	v_and_b32_e32 v134, 0xffff0000, v115
	v_fmac_f32_e32 v132, v133, v133
	v_fmac_f32_e32 v132, v134, v134
	s_nop 1
	v_add_f32_dpp v132, v132, v132 row_ror:8 row_mask:0xf bank_mask:0xf
	s_nop 1
	v_add_f32_dpp v132, v132, v132 row_ror:4 row_mask:0xf bank_mask:0xf
	s_nop 1
	v_add_f32_dpp v132, v132, v132 row_ror:2 row_mask:0xf bank_mask:0xf
	s_nop 1
	v_add_f32_dpp v132, v132, v132 row_ror:1 row_mask:0xf bank_mask:0xf
	v_max_f32_e32 v135, v135, v132
	s_waitcnt vmcnt(3)
	v_lshlrev_b32_e32 v133, 16, v116
	v_and_b32_e32 v134, 0xffff0000, v116
	v_mul_f32_e32 v132, v133, v133
	v_fmac_f32_e32 v132, v134, v134
	v_lshlrev_b32_e32 v133, 16, v117
	v_and_b32_e32 v134, 0xffff0000, v117
	v_fmac_f32_e32 v132, v133, v133
	v_fmac_f32_e32 v132, v134, v134
	v_lshlrev_b32_e32 v133, 16, v118
	v_and_b32_e32 v134, 0xffff0000, v118
	v_fmac_f32_e32 v132, v133, v133
	v_fmac_f32_e32 v132, v134, v134
	v_lshlrev_b32_e32 v133, 16, v119
	v_and_b32_e32 v134, 0xffff0000, v119
	v_fmac_f32_e32 v132, v133, v133
	v_fmac_f32_e32 v132, v134, v134
	s_nop 1
	v_add_f32_dpp v132, v132, v132 row_ror:8 row_mask:0xf bank_mask:0xf
	s_nop 1
	v_add_f32_dpp v132, v132, v132 row_ror:4 row_mask:0xf bank_mask:0xf
	s_nop 1
	v_add_f32_dpp v132, v132, v132 row_ror:2 row_mask:0xf bank_mask:0xf
	s_nop 1
	v_add_f32_dpp v132, v132, v132 row_ror:1 row_mask:0xf bank_mask:0xf
	v_max_f32_e32 v135, v135, v132
	s_waitcnt vmcnt(2)
	v_lshlrev_b32_e32 v133, 16, v120
	v_and_b32_e32 v134, 0xffff0000, v120
	v_mul_f32_e32 v132, v133, v133
	v_fmac_f32_e32 v132, v134, v134
	v_lshlrev_b32_e32 v133, 16, v121
	v_and_b32_e32 v134, 0xffff0000, v121
	v_fmac_f32_e32 v132, v133, v133
	v_fmac_f32_e32 v132, v134, v134
	v_lshlrev_b32_e32 v133, 16, v122
	v_and_b32_e32 v134, 0xffff0000, v122
	v_fmac_f32_e32 v132, v133, v133
	v_fmac_f32_e32 v132, v134, v134
	v_lshlrev_b32_e32 v133, 16, v123
	v_and_b32_e32 v134, 0xffff0000, v123
	v_fmac_f32_e32 v132, v133, v133
	v_fmac_f32_e32 v132, v134, v134
	s_nop 1
	v_add_f32_dpp v132, v132, v132 row_ror:8 row_mask:0xf bank_mask:0xf
	s_nop 1
	v_add_f32_dpp v132, v132, v132 row_ror:4 row_mask:0xf bank_mask:0xf
	s_nop 1
	v_add_f32_dpp v132, v132, v132 row_ror:2 row_mask:0xf bank_mask:0xf
	s_nop 1
	v_add_f32_dpp v132, v132, v132 row_ror:1 row_mask:0xf bank_mask:0xf
	v_max_f32_e32 v135, v135, v132
	s_waitcnt vmcnt(1)
	v_lshlrev_b32_e32 v133, 16, v124
	v_and_b32_e32 v134, 0xffff0000, v124
	v_mul_f32_e32 v132, v133, v133
	v_fmac_f32_e32 v132, v134, v134
	v_lshlrev_b32_e32 v133, 16, v125
	v_and_b32_e32 v134, 0xffff0000, v125
	v_fmac_f32_e32 v132, v133, v133
	v_fmac_f32_e32 v132, v134, v134
	v_lshlrev_b32_e32 v133, 16, v126
	v_and_b32_e32 v134, 0xffff0000, v126
	v_fmac_f32_e32 v132, v133, v133
	v_fmac_f32_e32 v132, v134, v134
	v_lshlrev_b32_e32 v133, 16, v127
	v_and_b32_e32 v134, 0xffff0000, v127
	v_fmac_f32_e32 v132, v133, v133
	v_fmac_f32_e32 v132, v134, v134
	s_nop 1
	v_add_f32_dpp v132, v132, v132 row_ror:8 row_mask:0xf bank_mask:0xf
	s_nop 1
	v_add_f32_dpp v132, v132, v132 row_ror:4 row_mask:0xf bank_mask:0xf
	s_nop 1
	v_add_f32_dpp v132, v132, v132 row_ror:2 row_mask:0xf bank_mask:0xf
	s_nop 1
	v_add_f32_dpp v132, v132, v132 row_ror:1 row_mask:0xf bank_mask:0xf
	v_max_f32_e32 v135, v135, v132
	s_waitcnt vmcnt(0)
	v_lshlrev_b32_e32 v133, 16, v128
	v_and_b32_e32 v134, 0xffff0000, v128
	v_mul_f32_e32 v132, v133, v133
	v_fmac_f32_e32 v132, v134, v134
	v_lshlrev_b32_e32 v133, 16, v129
	v_and_b32_e32 v134, 0xffff0000, v129
	v_fmac_f32_e32 v132, v133, v133
	v_fmac_f32_e32 v132, v134, v134
	v_lshlrev_b32_e32 v133, 16, v130
	v_and_b32_e32 v134, 0xffff0000, v130
	v_fmac_f32_e32 v132, v133, v133
	v_fmac_f32_e32 v132, v134, v134
	v_lshlrev_b32_e32 v133, 16, v131
	v_and_b32_e32 v134, 0xffff0000, v131
	v_fmac_f32_e32 v132, v133, v133
	v_fmac_f32_e32 v132, v134, v134
	s_nop 1
	v_add_f32_dpp v132, v132, v132 row_ror:8 row_mask:0xf bank_mask:0xf
	s_nop 1
	v_add_f32_dpp v132, v132, v132 row_ror:4 row_mask:0xf bank_mask:0xf
	s_nop 1
	v_add_f32_dpp v132, v132, v132 row_ror:2 row_mask:0xf bank_mask:0xf
	s_nop 1
	v_add_f32_dpp v132, v132, v132 row_ror:1 row_mask:0xf bank_mask:0xf
	v_max_f32_e32 v135, v135, v132
	v_mov_b32_e32 v3, 0x1c010
	v_mov_b32_e32 v4, 0
	ds_write_b32 v3, v4
	s_waitcnt lgkmcnt(0)
	s_barrier
	ds_max_u32 v3, v135
	s_waitcnt lgkmcnt(0)
	s_barrier
	v_readfirstlane_b32 s96, v255
	s_cmp_lg_u32 s96, 0
	s_cbranch_scc1 .Lq_kdone
	s_mov_b64 s[96:97], exec
	s_mov_b64 exec, 1
	ds_read_b32 v4, v3
	v_mov_b32_e32 v5, s95
	s_waitcnt lgkmcnt(0)
	global_atomic_umax v6, v5, v4, s[90:91] sc0
	s_waitcnt vmcnt(0)
	v_mov_b32_e32 v5, 520
	v_mov_b32_e32 v4, 1
	global_atomic_add v6, v5, v4, s[90:91] sc0
	s_waitcnt vmcnt(0)
.Lq_kspin:
	global_load_dword v6, v5, s[90:91] sc1
	s_waitcnt vmcnt(0)
	v_readfirstlane_b32 s95, v6
	s_cmp_ge_u32 s95, s58
	s_cbranch_scc1 .Lq_kfin
	s_sleep 2
	s_branch .Lq_kspin
.Lq_kfin:
	s_mov_b64 exec, s[96:97]
.Lq_kdone:
	s_barrier
	s_getreg_b32 s92, hwreg(HW_REG_XCC_ID, 0, 4)
	s_and_b32 s92, s92, 7

.Lq_cl_done:
	s_lshr_b32 s95, s88, 3
	s_lshl_b32 s95, s95, 2
	s_addk_i32 s95, 640
	v_mov_b32_e32 v232, s95
	global_load_dword v233, v232, s[90:91] sc1
	v_mov_b32_e32 v18, v255
	s_and_b32 s50, s88, 7
	s_ashr_i32 s0, s88, 7
	s_mov_b32 s51, s94
	v_readfirstlane_b32 s5, v18
	s_ashr_i32 s1, s0, 31
	s_ashr_i32 s33, s5, 1
	s_lshl_b64 s[22:23], s[0:1], 12
	s_lshl_b32 s60, s51, 8
	s_andn2_b32 s33, s33, 31
	s_bfe_u32 s4, s88, 0x40003
	s_lshl_b64 s[6:7], s[0:1], 26
	s_or_b32 s1, s22, s60
	s_ashr_i32 s16, s33, 31
	s_add_u32 s24, s1, s33
	v_and_b32_e32 v30, 31, v18
	s_addc_u32 s25, s23, s16
	v_or_b32_e32 v2, s24, v30
	v_mov_b32_e32 v3, s25
	v_lshlrev_b64 v[2:3], 14, v[2:3]
	v_bfe_u32 v31, v18, 5, 1
	v_lshl_add_u64 v[2:3], s[12:13], 0, v[2:3]
	s_lshl_b32 s16, s4, 8
	v_lshl_add_u64 v[2:3], v[2:3], 0, s[16:17]
	v_lshlrev_b32_e32 v0, 4, v31
	v_ashrrev_i32_e32 v19, 31, v18
	v_lshl_add_u64 v[2:3], v[2:3], 0, v[0:1]
	v_lshrrev_b32_e32 v0, 28, v19
	s_add_u32 s1, s12, s6
	v_add_u32_e32 v0, v18, v0
	s_addc_u32 s6, s13, s7
	v_ashrrev_i32_e32 v146, 4, v0
	v_and_b32_e32 v0, -16, v0
	s_add_u32 s20, s1, s16
	v_sub_u32_e32 v0, v18, v0
	v_ashrrev_i32_e32 v147, 31, v146
	global_load_dwordx4 v[98:101], v[2:3], off
	global_load_dwordx4 v[102:105], v[2:3], off offset:32
	global_load_dwordx4 v[106:109], v[2:3], off offset:64
	global_load_dwordx4 v[110:113], v[2:3], off offset:96
	global_load_dwordx4 v[114:117], v[2:3], off offset:128
	global_load_dwordx4 v[118:121], v[2:3], off offset:160
	global_load_dwordx4 v[122:125], v[2:3], off offset:192
	global_load_dwordx4 v[126:129], v[2:3], off offset:224
	s_addc_u32 s21, s6, 0
	v_lshlrev_b64 v[2:3], 14, v[146:147]
	v_lshlrev_b32_e32 v20, 3, v0
	s_lshl_b32 s84, s51, 22
	s_add_u32 s84, s84, 0x300000
	s_add_u32 s84, s20, s84
	s_addc_u32 s85, s21, 0
	s_sub_u32 s86, s84, 0x200000
	s_subb_u32 s87, s85, 0
	v_lshl_add_u64 v[2:3], s[84:85], 0, v[2:3]
	v_ashrrev_i32_e32 v21, 31, v20
	v_lshl_add_u64 v[2:3], v[20:21], 1, v[2:3]
	v_add_co_u32_e32 v2, vcc, s43, v2
	s_cmp_gt_u32 s5, 63
	s_nop 0
	v_addc_co_u32_e32 v3, vcc, 0, v3, vcc
	global_load_dwordx4 v[14:17], v[2:3], off offset:-4096
	global_load_dwordx4 v[10:13], v[2:3], off
	v_add_u32_e32 v2, 0x200, v18
	v_ashrrev_i32_e32 v3, 31, v2
	v_lshrrev_b32_e32 v3, 28, v3
	v_add_u32_e32 v3, v2, v3
	v_ashrrev_i32_e32 v148, 4, v3
	v_and_b32_e32 v3, -16, v3
	v_sub_u32_e32 v32, v2, v3
	v_ashrrev_i32_e32 v149, 31, v148
	v_lshlrev_b64 v[2:3], 14, v[148:149]
	v_lshlrev_b32_e32 v22, 3, v32
	v_lshl_add_u64 v[2:3], s[84:85], 0, v[2:3]
	v_ashrrev_i32_e32 v23, 31, v22
	v_lshl_add_u64 v[2:3], v[22:23], 1, v[2:3]
	v_add_co_u32_e32 v4, vcc, 0x1000, v2
	v_and_b32_e32 v156, 63, v18
	s_nop 0
	v_addc_co_u32_e32 v5, vcc, 0, v3, vcc
	v_add_co_u32_e32 v6, vcc, 0x2000, v2
	s_nop 1
	v_addc_co_u32_e32 v7, vcc, 0, v3, vcc
	global_load_dwordx4 v[2:5], v[4:5], off
	s_nop 0
	global_load_dwordx4 v[6:9], v[6:7], off
	s_cbranch_scc1 .LBB0_628
	s_lshl_b32 s1, s0, 10
	v_lshl_or_b32 v24, v156, 4, s1
	v_or_b32_e32 v24, s4, v24
	v_ashrrev_i32_e32 v25, 31, v24
	v_lshl_add_u64 v[24:25], v[24:25], 2, s[14:15]
	global_load_dword v24, v[24:25], off
	v_and_b32_e32 v25, 64, v154
	v_add_u32_e32 v26, -1, v154
	v_cmp_lt_i32_e32 vcc, v26, v25
	v_add_u32_e32 v27, -2, v154
	v_add_u32_e32 v28, -4, v154
	v_cndmask_b32_e32 v26, v26, v154, vcc
	v_lshlrev_b32_e32 v26, 2, v26
	v_cmp_lt_i32_e32 vcc, v27, v25
	s_waitcnt vmcnt(0)
	ds_bpermute_b32 v26, v26, v24
	v_cndmask_b32_e32 v27, v27, v154, vcc
	v_cmp_eq_u32_e32 vcc, 0, v156
	v_lshlrev_b32_e32 v27, 2, v27
	s_waitcnt lgkmcnt(0)
	v_add_f32_e32 v26, v24, v26
	v_cndmask_b32_e32 v26, v26, v24, vcc
	ds_bpermute_b32 v27, v27, v26
	v_cmp_lt_i32_e32 vcc, v28, v25
	s_waitcnt lgkmcnt(0)
	v_add_f32_e32 v27, v26, v27
	v_cndmask_b32_e32 v28, v28, v154, vcc
	v_cmp_gt_u32_e32 vcc, 2, v156
	v_lshlrev_b32_e32 v28, 2, v28
	s_nop 0
	v_cndmask_b32_e32 v26, v27, v26, vcc
	ds_bpermute_b32 v27, v28, v26
	v_add_u32_e32 v28, -8, v154
	v_cmp_lt_i32_e32 vcc, v28, v25
	s_waitcnt lgkmcnt(0)
	v_add_f32_e32 v27, v26, v27
	v_cndmask_b32_e32 v28, v28, v154, vcc
	v_cmp_gt_u32_e32 vcc, 4, v156
	v_lshlrev_b32_e32 v28, 2, v28
	s_nop 0
	v_cndmask_b32_e32 v26, v27, v26, vcc
	ds_bpermute_b32 v27, v28, v26
	v_add_u32_e32 v28, -16, v154
	v_cmp_lt_i32_e32 vcc, v28, v25
	s_waitcnt lgkmcnt(0)
	v_add_f32_e32 v27, v26, v27
	v_cndmask_b32_e32 v28, v28, v154, vcc
	v_cmp_gt_u32_e32 vcc, 8, v156
	v_lshlrev_b32_e32 v28, 2, v28
	s_nop 0
	v_cndmask_b32_e32 v26, v27, v26, vcc
	ds_bpermute_b32 v27, v28, v26
	v_subrev_u32_e32 v28, 32, v154
	v_cmp_lt_i32_e32 vcc, v28, v25
	s_waitcnt lgkmcnt(0)
	v_add_f32_e32 v27, v26, v27
	v_cndmask_b32_e32 v25, v28, v154, vcc
	v_cmp_gt_u32_e32 vcc, 16, v156
	v_lshlrev_b32_e32 v25, 2, v25
	s_nop 0
	v_cndmask_b32_e32 v26, v27, v26, vcc
	ds_bpermute_b32 v25, v25, v26
	v_cmp_gt_u32_e32 vcc, 32, v156
	v_lshl_add_u32 v27, v156, 2, 0
	s_waitcnt lgkmcnt(0)
	v_add_f32_e32 v25, v26, v25
	v_cndmask_b32_e32 v25, v25, v26, vcc
	v_sub_f32_e32 v24, v25, v24
	v_add_u32_e32 v25, 0x16800, v27
	ds_write_b32 v25, v24

.Lq_w1:
	v_and_b32_e32 v252, 63, v255
	v_lshlrev_b32_e32 v252, 2, v252
	v_add_u32_e32 v252, 0x1c100, v252
	v_mov_b32_e32 v153, 0
	ds_write_b32 v252, v153
	v_mov_b32_e32 v151, 0
	v_lshlrev_b32_e32 v252, 16, v98
	v_and_b32_e32 v253, 0xffff0000, v98
	v_fmac_f32_e32 v151, v252, v252
	v_fmac_f32_e32 v151, v253, v253
	v_lshlrev_b32_e32 v252, 16, v99
	v_and_b32_e32 v253, 0xffff0000, v99
	v_fmac_f32_e32 v151, v252, v252
	v_fmac_f32_e32 v151, v253, v253
	v_lshlrev_b32_e32 v252, 16, v100
	v_and_b32_e32 v253, 0xffff0000, v100
	v_fmac_f32_e32 v151, v252, v252
	v_fmac_f32_e32 v151, v253, v253
	v_lshlrev_b32_e32 v252, 16, v101
	v_and_b32_e32 v253, 0xffff0000, v101
	v_fmac_f32_e32 v151, v252, v252
	v_fmac_f32_e32 v151, v253, v253
	v_lshlrev_b32_e32 v252, 16, v102
	v_and_b32_e32 v253, 0xffff0000, v102
	v_fmac_f32_e32 v151, v252, v252
	v_fmac_f32_e32 v151, v253, v253
	v_lshlrev_b32_e32 v252, 16, v103
	v_and_b32_e32 v253, 0xffff0000, v103
	v_fmac_f32_e32 v151, v252, v252
	v_fmac_f32_e32 v151, v253, v253
	v_lshlrev_b32_e32 v252, 16, v104
	v_and_b32_e32 v253, 0xffff0000, v104
	v_fmac_f32_e32 v151, v252, v252
	v_fmac_f32_e32 v151, v253, v253
	v_lshlrev_b32_e32 v252, 16, v105
	v_and_b32_e32 v253, 0xffff0000, v105
	v_fmac_f32_e32 v151, v252, v252
	v_fmac_f32_e32 v151, v253, v253
	v_lshlrev_b32_e32 v252, 16, v106
	v_and_b32_e32 v253, 0xffff0000, v106
	v_fmac_f32_e32 v151, v252, v252
	v_fmac_f32_e32 v151, v253, v253
	v_lshlrev_b32_e32 v252, 16, v107
	v_and_b32_e32 v253, 0xffff0000, v107
	v_fmac_f32_e32 v151, v252, v252
	v_fmac_f32_e32 v151, v253, v253
	v_lshlrev_b32_e32 v252, 16, v108
	v_and_b32_e32 v253, 0xffff0000, v108
	v_fmac_f32_e32 v151, v252, v252
	v_fmac_f32_e32 v151, v253, v253
	v_lshlrev_b32_e32 v252, 16, v109
	v_and_b32_e32 v253, 0xffff0000, v109
	v_fmac_f32_e32 v151, v252, v252
	v_fmac_f32_e32 v151, v253, v253
	v_lshlrev_b32_e32 v252, 16, v110
	v_and_b32_e32 v253, 0xffff0000, v110
	v_fmac_f32_e32 v151, v252, v252
	v_fmac_f32_e32 v151, v253, v253
	v_lshlrev_b32_e32 v252, 16, v111
	v_and_b32_e32 v253, 0xffff0000, v111
	v_fmac_f32_e32 v151, v252, v252
	v_fmac_f32_e32 v151, v253, v253
	v_lshlrev_b32_e32 v252, 16, v112
	v_and_b32_e32 v253, 0xffff0000, v112
	v_fmac_f32_e32 v151, v252, v252
	v_fmac_f32_e32 v151, v253, v253
	v_lshlrev_b32_e32 v252, 16, v113
	v_and_b32_e32 v253, 0xffff0000, v113
	v_fmac_f32_e32 v151, v252, v252
	v_fmac_f32_e32 v151, v253, v253
	v_lshlrev_b32_e32 v252, 16, v114
	v_and_b32_e32 v253, 0xffff0000, v114
	v_fmac_f32_e32 v151, v252, v252
	v_fmac_f32_e32 v151, v253, v253
	v_lshlrev_b32_e32 v252, 16, v115
	v_and_b32_e32 v253, 0xffff0000, v115
	v_fmac_f32_e32 v151, v252, v252
	v_fmac_f32_e32 v151, v253, v253
	v_lshlrev_b32_e32 v252, 16, v116
	v_and_b32_e32 v253, 0xffff0000, v116
	v_fmac_f32_e32 v151, v252, v252
	v_fmac_f32_e32 v151, v253, v253
	v_lshlrev_b32_e32 v252, 16, v117
	v_and_b32_e32 v253, 0xffff0000, v117
	v_fmac_f32_e32 v151, v252, v252
	v_fmac_f32_e32 v151, v253, v253
	v_lshlrev_b32_e32 v252, 16, v118
	v_and_b32_e32 v253, 0xffff0000, v118
	v_fmac_f32_e32 v151, v252, v252
	v_fmac_f32_e32 v151, v253, v253
	v_lshlrev_b32_e32 v252, 16, v119
	v_and_b32_e32 v253, 0xffff0000, v119
	v_fmac_f32_e32 v151, v252, v252
	v_fmac_f32_e32 v151, v253, v253
	v_lshlrev_b32_e32 v252, 16, v120
	v_and_b32_e32 v253, 0xffff0000, v120
	v_fmac_f32_e32 v151, v252, v252
	v_fmac_f32_e32 v151, v253, v253
	v_lshlrev_b32_e32 v252, 16, v121
	v_and_b32_e32 v253, 0xffff0000, v121
	v_fmac_f32_e32 v151, v252, v252
	v_fmac_f32_e32 v151, v253, v253
	v_lshlrev_b32_e32 v252, 16, v122
	v_and_b32_e32 v253, 0xffff0000, v122
	v_fmac_f32_e32 v151, v252, v252
	v_fmac_f32_e32 v151, v253, v253
	v_lshlrev_b32_e32 v252, 16, v123
	v_and_b32_e32 v253, 0xffff0000, v123
	v_fmac_f32_e32 v151, v252, v252
	v_fmac_f32_e32 v151, v253, v253
	v_lshlrev_b32_e32 v252, 16, v124
	v_and_b32_e32 v253, 0xffff0000, v124
	v_fmac_f32_e32 v151, v252, v252
	v_fmac_f32_e32 v151, v253, v253
	v_lshlrev_b32_e32 v252, 16, v125
	v_and_b32_e32 v253, 0xffff0000, v125
	v_fmac_f32_e32 v151, v252, v252
	v_fmac_f32_e32 v151, v253, v253
	v_lshlrev_b32_e32 v252, 16, v126
	v_and_b32_e32 v253, 0xffff0000, v126
	v_fmac_f32_e32 v151, v252, v252
	v_fmac_f32_e32 v151, v253, v253
	v_lshlrev_b32_e32 v252, 16, v127
	v_and_b32_e32 v253, 0xffff0000, v127
	v_fmac_f32_e32 v151, v252, v252
	v_fmac_f32_e32 v151, v253, v253
	v_lshlrev_b32_e32 v252, 16, v128
	v_and_b32_e32 v253, 0xffff0000, v128
	v_fmac_f32_e32 v151, v252, v252
	v_fmac_f32_e32 v151, v253, v253
	v_lshlrev_b32_e32 v252, 16, v129
	v_and_b32_e32 v253, 0xffff0000, v129
	v_fmac_f32_e32 v151, v252, v252
	v_fmac_f32_e32 v151, v253, v253
	s_nop 1
	v_mov_b32_e32 v252, v151
	v_nop
	v_nop
	v_permlane32_swap_b32 v151, v252
	s_nop 1
	v_add_f32_e32 v151, v151, v252
	v_mul_f32_e32 v151, v151, v233
	v_sqrt_f32_e32 v151, v151
	s_nop 1
	v_mul_f32_e32 v151, 0x3f804189, v151
	ds_write_b128 v0, v[14:17]
	v_mad_u64_u32 v[14:15], s[4:5], v146, 48, v[0:1]
	ds_write_b128 v14, v[10:13] offset:34816
	v_lshlrev_b64 v[10:11], 14, v[146:147]
	v_lshl_add_u64 v[10:11], s[86:87], 0, v[10:11]
	v_lshlrev_b64 v[12:13], 1, v[20:21]
	v_lshl_add_u64 v[10:11], v[10:11], 0, v[12:13]
	v_add_co_u32_e32 v10, vcc, s47, v10
	v_lshlrev_b64 v[14:15], 1, v[22:23]
	s_nop 0
	v_addc_co_u32_e32 v11, vcc, 0, v11, vcc
	global_load_dwordx4 v[130:133], v[10:11], off offset:-4096
	global_load_dwordx4 v[134:137], v[10:11], off
	v_lshlrev_b64 v[10:11], 14, v[148:149]
	v_lshl_add_u64 v[10:11], s[86:87], 0, v[10:11]
	v_lshl_add_u64 v[10:11], v[10:11], 0, v[14:15]
	v_add_co_u32_e32 v10, vcc, s47, v10
	v_mul_lo_u32 v160, v148, s45
	s_nop 0
	v_addc_co_u32_e32 v11, vcc, 0, v11, vcc
	global_load_dwordx4 v[138:141], v[10:11], off offset:-4096
	global_load_dwordx4 v[142:145], v[10:11], off
	v_lshlrev_b32_e32 v161, 4, v32
	v_add3_u32 v0, 0, v160, v161
	ds_write_b128 v0, v[2:5]
	v_mad_u64_u32 v[2:3], s[4:5], v148, 48, v[0:1]
	v_lshrrev_b32_e32 v0, 2, v18
	v_lshlrev_b32_e32 v163, 2, v31
	ds_write_b128 v2, v[6:9] offset:34816
	v_and_or_b32 v0, v0, 3, v163
	v_lshlrev_b32_e32 v2, 1, v18
	v_lshlrev_b32_e32 v3, 3, v18
	s_add_i32 s5, s33, s60
	v_lshl_add_u32 v149, v31, 4, 0
	v_mad_u32_u24 v0, v0, s46, 0
	v_and_b32_e32 v2, 32, v2
	v_and_b32_e32 v3, 24, v3
	v_lshl_add_u32 v152, v148, 14, v14
	v_mov_b32_e32 v14, v1
	v_mov_b32_e32 v15, v1
	v_mad_u32_u24 v162, v30, s45, v149
	v_add3_u32 v164, v0, v2, v3
	v_lshl_add_u32 v150, v146, 14, v12
	s_mov_b64 s[78:79], s[20:21]
	v_add_u32_e32 v195, s5, v30
	v_mov_b32_e32 v0, v1
	v_mov_b32_e32 v2, v1
	v_mov_b32_e32 v3, v1
	v_mov_b32_e32 v4, v1
	v_mov_b32_e32 v5, v1
	v_mov_b32_e32 v6, v1
	v_mov_b32_e32 v7, v1
	v_mov_b32_e32 v8, v1
	v_mov_b32_e32 v9, v1
	v_mov_b32_e32 v10, v1
	v_mov_b32_e32 v11, v1
	v_mov_b32_e32 v12, v1
	v_mov_b32_e32 v13, v1
	v_mov_b64_e32 v[64:65], v[14:15]
	v_mov_b64_e32 v[48:49], v[14:15]
	v_mov_b64_e32 v[32:33], v[14:15]
	s_lshl_b32 s6, s51, 2
	s_lshl_b32 s7, s51, 10
	v_mov_b64_e32 v[62:63], v[12:13]
	v_mov_b64_e32 v[60:61], v[10:11]
	v_mov_b64_e32 v[58:59], v[8:9]
	v_mov_b64_e32 v[56:57], v[6:7]
	v_mov_b64_e32 v[54:55], v[4:5]
	v_mov_b64_e32 v[52:53], v[2:3]
	v_mov_b64_e32 v[50:51], v[0:1]
	v_mov_b64_e32 v[46:47], v[12:13]
	v_mov_b64_e32 v[44:45], v[10:11]
	v_mov_b64_e32 v[42:43], v[8:9]
	v_mov_b64_e32 v[40:41], v[6:7]
	v_mov_b64_e32 v[38:39], v[4:5]
	v_mov_b64_e32 v[36:37], v[2:3]
	v_mov_b64_e32 v[34:35], v[0:1]
	v_mov_b64_e32 v[30:31], v[12:13]
	v_mov_b64_e32 v[28:29], v[10:11]
	v_mov_b64_e32 v[26:27], v[8:9]
	v_mov_b64_e32 v[24:25], v[6:7]
	v_mov_b64_e32 v[22:23], v[4:5]
	v_mov_b64_e32 v[20:21], v[2:3]
	v_mov_b64_e32 v[18:19], v[0:1]
	v_mov_b64_e32 v[16:17], v[14:15]
	s_mov_b32 s0, 2
	s_add_i32 s1, s6, 4
	v_mul_lo_u32 v159, v146, s46
	v_mul_lo_u32 v147, v148, s46
	s_mov_b32 s4, 0
	s_or_b32 s6, s6, 3
	v_or_b32_e32 v165, 32, v163
	v_or_b32_e32 v166, 33, v163
	v_or_b32_e32 v167, 2, v163
	v_or_b32_e32 v168, 34, v163
	v_or_b32_e32 v169, 3, v163
	v_or_b32_e32 v170, 35, v163
	v_or_b32_e32 v171, 8, v163
	v_or_b32_e32 v172, 40, v163
	v_or_b32_e32 v173, 9, v163
	v_or_b32_e32 v174, 41, v163
	v_or_b32_e32 v175, 10, v163
	v_or_b32_e32 v176, 42, v163
	v_or_b32_e32 v177, 11, v163
	v_or_b32_e32 v178, 43, v163
	v_or_b32_e32 v179, 16, v163
	v_or_b32_e32 v180, 48, v163
	v_or_b32_e32 v181, 17, v163
	v_or_b32_e32 v182, 49, v163
	v_or_b32_e32 v183, 18, v163
	v_or_b32_e32 v184, 50, v163
	v_or_b32_e32 v185, 19, v163
	v_or_b32_e32 v186, 51, v163
	v_or_b32_e32 v187, 24, v163
	v_or_b32_e32 v188, 56, v163
	v_or_b32_e32 v189, 25, v163
	v_or_b32_e32 v190, 57, v163
	v_or_b32_e32 v191, 26, v163
	v_or_b32_e32 v192, 58, v163
	v_or_b32_e32 v193, 27, v163
	v_or_b32_e32 v194, 59, v163
	s_addk_i32 s7, 0x400
	v_mov_b32_e32 v196, 0
	v_mov_b32_e32 v197, 0xf149f2ca
	s_mov_b32 s26, 63
	v_mov_b64_e32 v[14:15], v[12:13]
	v_mov_b64_e32 v[12:13], v[10:11]
	v_mov_b64_e32 v[10:11], v[8:9]
	v_mov_b64_e32 v[8:9], v[6:7]
	v_mov_b64_e32 v[6:7], v[4:5]
	v_mov_b64_e32 v[4:5], v[2:3]
	v_mov_b64_e32 v[2:3], v[0:1]
	s_waitcnt lgkmcnt(0)
	s_movk_i32 s68, 0x5000
	s_mov_b32 s69, 0
	s_mov_b32 s70, 0xe800
	s_mov_b32 s72, 0
	s_lshl_b32 s77, s6, 6
	v_subrev_u32_e32 v195, s77, v195
	s_barrier
	v_readfirstlane_b32 s73, v255
	s_cmp_lt_u32 s73, 0x100
	s_cbranch_scc1 .Lyp649
	s_setprio 1
.Lyp649:
	s_mov_b32 s74, s5
	s_branch .LBB0_649
.LBB0_649:
	s_add_i32 s27, s0, -2
	s_and_b32 s27, s27, 1
	s_xor_b32 s34, s27, 1
	s_mul_i32 s35, s34, 0x4400
	s_add_i32 s35, s35, 0
	s_mulk_i32 s34, 0xc00
	s_add_i32 s34, s35, s34
	v_add3_u32 v0, s35, v157, v158
	s_waitcnt vmcnt(3)
	ds_write_b128 v0, v[130:133]
	v_add3_u32 v0, s68, v159, v158
	s_waitcnt vmcnt(2)
	ds_write_b128 v0, v[134:137] offset:34816
	v_add3_u32 v0, s35, v160, v161
	s_cmp_lt_u32 s0, s1
	s_waitcnt vmcnt(1)
	ds_write_b128 v0, v[138:141]
	v_add3_u32 v0, s68, v147, v161
	s_cselect_b32 s34, s0, s6
	s_sub_i32 s34, s6, s34
	s_lshl_b32 s34, s34, 20
	s_add_u32 s80, s78, s34
	s_addc_u32 s81, s79, 0
	s_add_u32 s80, s80, 0x1000
	s_addc_u32 s81, s81, 0
	s_add_u32 s82, s80, 0x1000
	s_addc_u32 s83, s81, 0
	s_waitcnt vmcnt(0)
	ds_write_b128 v0, v[142:145] offset:34816
	global_load_dwordx4 v[130:133], v150, s[80:81]
	global_load_dwordx4 v[134:137], v150, s[82:83]
	s_sub_i32 s34, s26, 63
	s_cmp_gt_i32 s34, s5
	global_load_dwordx4 v[138:141], v152, s[80:81]
	global_load_dwordx4 v[142:145], v152, s[82:83]
	s_lshr_b32 s77, s7, 2
	s_sub_i32 s77, s77, s26
	s_add_i32 s77, s77, -1
	s_sub_i32 s75, s7, s4
	s_add_i32 s75, s75, -256
	s_waitcnt lgkmcnt(4)
	v_readfirstlane_b32 s86, v153
	s_cmpk_eq_u32 s86, 0x200
	s_cbranch_scc1 .Lff1a_exit
	s_cmp_gt_i32 s77, s74
	s_cbranch_scc1 .Lff1a_inact
	s_cmp_eq_u32 s72, 0
	s_cbranch_scc1 .Lff1a_first
	s_mul_i32 s34, s27, 0x4400
	v_add_u32_e32 v0, s34, v162
	ds_read_b128 v[198:201], v0
	ds_read_b128 v[202:205], v0 offset:32
	ds_read_b128 v[206:209], v0 offset:8704
	ds_read_b128 v[210:213], v0 offset:8736
	v_add_u32_e32 v246, s75, v149
	v_add_u32_e32 v234, 0x12800, v246
	v_add_u32_e32 v235, 0x12880, v246
	v_add_u32_e32 v238, 0x12820, v246
	v_add_u32_e32 v239, 0x128a0, v246
	v_add_u32_e32 v242, 0x12840, v246
	v_add_u32_e32 v243, 0x128c0, v246
	v_add_u32_e32 v247, 0x12860, v246
	v_add_u32_e32 v246, 0x128e0, v246
	ds_read_b128 v[218:221], v234
	ds_read_b128 v[234:237], v235
	ds_read_b128 v[222:225], v238
	ds_read_b128 v[238:241], v239
	ds_read_b128 v[226:229], v242
	ds_read_b128 v[242:245], v243
	ds_read_b128 v[230:233], v247
	ds_read_b128 v[246:249], v246
	s_waitcnt lgkmcnt(1)
	v_mfma_f32_32x32x16_bf16 v[218:233], v[198:201], v[98:101], v[218:233]
	v_sub_f32_e32 v82, v82, v197
	v_sub_f32_e32 v83, v83, v197
	v_sub_f32_e32 v84, v84, v197
	v_sub_f32_e32 v85, v85, v197
	v_exp_f32_e32 v82, v82
	v_exp_f32_e32 v83, v83
	v_exp_f32_e32 v84, v84
	v_exp_f32_e32 v85, v85
	s_waitcnt lgkmcnt(0)
	v_mfma_f32_32x32x16_bf16 v[234:249], v[206:209], v[98:101], v[234:249]
	v_sub_f32_e32 v86, v86, v197
	v_sub_f32_e32 v87, v87, v197
	v_sub_f32_e32 v88, v88, v197
	v_sub_f32_e32 v89, v89, v197
	v_exp_f32_e32 v86, v86
	v_exp_f32_e32 v87, v87
	v_exp_f32_e32 v88, v88
	v_exp_f32_e32 v89, v89
	v_mfma_f32_32x32x16_bf16 v[218:233], v[202:205], v[102:105], v[218:233]
	v_sub_f32_e32 v66, v66, v197
	v_sub_f32_e32 v67, v67, v197
	v_sub_f32_e32 v68, v68, v197
	v_sub_f32_e32 v69, v69, v197
	v_exp_f32_e32 v66, v66
	v_exp_f32_e32 v67, v67
	v_exp_f32_e32 v68, v68
	v_exp_f32_e32 v69, v69
	ds_read_b128 v[198:201], v0 offset:64
	ds_read_b128 v[202:205], v0 offset:96
	ds_read_b128 v[206:209], v0 offset:8768
	ds_read_b128 v[214:217], v0 offset:8800
	v_mfma_f32_32x32x16_bf16 v[234:249], v[210:213], v[102:105], v[234:249]
	v_add_f32_e32 v250, v82, v86
	v_add_f32_e32 v251, v83, v87
	v_add_f32_e32 v252, v84, v88
	v_add_f32_e32 v253, v85, v89
	v_sub_f32_e32 v70, v70, v197
	v_sub_f32_e32 v71, v71, v197
	v_sub_f32_e32 v72, v72, v197
	v_sub_f32_e32 v73, v73, v197
	s_waitcnt lgkmcnt(3)
	v_mfma_f32_32x32x16_bf16 v[218:233], v[198:201], v[106:109], v[218:233]
	v_exp_f32_e32 v70, v70
	v_exp_f32_e32 v71, v71
	v_exp_f32_e32 v72, v72
	v_exp_f32_e32 v73, v73
	v_add_f32_e32 v250, v250, v66
	v_add_f32_e32 v251, v251, v67
	v_add_f32_e32 v252, v252, v68
	v_add_f32_e32 v253, v253, v69
	s_waitcnt lgkmcnt(1)
	v_mfma_f32_32x32x16_bf16 v[234:249], v[206:209], v[106:109], v[234:249]
	v_sub_f32_e32 v90, v90, v197
	v_sub_f32_e32 v91, v91, v197
	v_sub_f32_e32 v92, v92, v197
	v_sub_f32_e32 v93, v93, v197
	v_exp_f32_e32 v90, v90
	v_exp_f32_e32 v91, v91
	v_exp_f32_e32 v92, v92
	v_exp_f32_e32 v93, v93
	v_mfma_f32_32x32x16_bf16 v[218:233], v[202:205], v[110:113], v[218:233]
	v_add_f32_e32 v250, v250, v70
	v_add_f32_e32 v251, v251, v71
	v_add_f32_e32 v252, v252, v72
	v_add_f32_e32 v253, v253, v73
	v_sub_f32_e32 v94, v94, v197
	v_sub_f32_e32 v95, v95, v197
	v_sub_f32_e32 v96, v96, v197
	v_sub_f32_e32 v97, v97, v197
	ds_read_b128 v[198:201], v0 offset:128
	ds_read_b128 v[202:205], v0 offset:160
	ds_read_b128 v[206:209], v0 offset:8832
	ds_read_b128 v[210:213], v0 offset:8864
	s_waitcnt lgkmcnt(4)
	v_mfma_f32_32x32x16_bf16 v[234:249], v[214:217], v[110:113], v[234:249]
	v_exp_f32_e32 v94, v94
	v_exp_f32_e32 v95, v95
	v_exp_f32_e32 v96, v96
	v_exp_f32_e32 v97, v97
	v_add_f32_e32 v250, v250, v90
	v_add_f32_e32 v251, v251, v91
	v_add_f32_e32 v252, v252, v92
	v_add_f32_e32 v253, v253, v93
	s_waitcnt lgkmcnt(3)
	v_mfma_f32_32x32x16_bf16 v[218:233], v[198:201], v[114:117], v[218:233]
	v_sub_f32_e32 v74, v74, v197
	v_sub_f32_e32 v75, v75, v197
	v_sub_f32_e32 v76, v76, v197
	v_sub_f32_e32 v77, v77, v197
	v_exp_f32_e32 v74, v74
	v_exp_f32_e32 v75, v75
	v_exp_f32_e32 v76, v76
	v_exp_f32_e32 v77, v77
	s_waitcnt lgkmcnt(1)
	v_mfma_f32_32x32x16_bf16 v[234:249], v[206:209], v[114:117], v[234:249]
	v_add_f32_e32 v250, v250, v94
	v_add_f32_e32 v251, v251, v95
	v_add_f32_e32 v252, v252, v96
	v_add_f32_e32 v253, v253, v97
	v_sub_f32_e32 v78, v78, v197
	v_sub_f32_e32 v79, v79, v197
	v_sub_f32_e32 v80, v80, v197
	v_sub_f32_e32 v81, v81, v197
	v_mfma_f32_32x32x16_bf16 v[218:233], v[202:205], v[118:121], v[218:233]
	v_exp_f32_e32 v78, v78
	v_exp_f32_e32 v79, v79
	v_exp_f32_e32 v80, v80
	v_exp_f32_e32 v81, v81
	v_add_f32_e32 v250, v250, v74
	v_add_f32_e32 v251, v251, v75
	v_add_f32_e32 v252, v252, v76
	v_add_f32_e32 v253, v253, v77
	ds_read_b128 v[198:201], v0 offset:192
	ds_read_b128 v[202:205], v0 offset:224
	ds_read_b128 v[206:209], v0 offset:8896
	ds_read_b128 v[214:217], v0 offset:8928
	s_waitcnt lgkmcnt(4)
	v_mfma_f32_32x32x16_bf16 v[234:249], v[210:213], v[118:121], v[234:249]
	v_add_f32_e32 v250, v250, v78
	v_add_f32_e32 v251, v251, v79
	v_add_f32_e32 v252, v252, v80
	v_add_f32_e32 v253, v253, v81
	v_add_f32_e32 v250, v250, v251
	v_add_f32_e32 v252, v252, v253
	v_add_f32_e32 v250, v250, v252
	v_add_f32_e32 v196, v196, v250
	s_waitcnt lgkmcnt(3)
	v_mfma_f32_32x32x16_bf16 v[218:233], v[198:201], v[122:125], v[218:233]
	v_cvt_pk_bf16_f32 v73, v72, v73
	v_cvt_pk_bf16_f32 v72, v70, v71
	v_cvt_pk_bf16_f32 v71, v68, v69
	v_cvt_pk_bf16_f32 v70, v66, v67
	v_cvt_pk_bf16_f32 v66, v82, v83
	v_cvt_pk_bf16_f32 v67, v84, v85
	v_cvt_pk_bf16_f32 v68, v86, v87
	v_cvt_pk_bf16_f32 v69, v88, v89
	s_waitcnt lgkmcnt(1)
	v_mfma_f32_32x32x16_bf16 v[234:249], v[206:209], v[122:125], v[234:249]
	v_cvt_pk_bf16_f32 v81, v80, v81
	v_cvt_pk_bf16_f32 v80, v78, v79
	v_cvt_pk_bf16_f32 v79, v76, v77
	v_cvt_pk_bf16_f32 v78, v74, v75
	v_cvt_pk_bf16_f32 v74, v90, v91
	v_cvt_pk_bf16_f32 v75, v92, v93
	v_cvt_pk_bf16_f32 v76, v94, v95
	v_cvt_pk_bf16_f32 v77, v96, v97
	v_mfma_f32_32x32x16_bf16 v[218:233], v[202:205], v[126:129], v[218:233]
	s_waitcnt lgkmcnt(0)
	v_mfma_f32_32x32x16_bf16 v[234:249], v[214:217], v[126:129], v[234:249]
	s_add_i32 s76, s77, 63
	s_cmp_le_i32 s76, s5
	s_cbranch_scc1 .Lff1a_z2
	v_cmp_le_i32_e32 vcc, v165, v195
	s_nop 8
	v_cndmask_b32_e32 v234, v155, v234, vcc
	v_cmp_lt_i32_e32 vcc, v163, v195
	s_nop 1
	v_cndmask_b32_e32 v219, v155, v219, vcc
	v_cmp_le_i32_e32 vcc, v163, v195
	s_nop 1
	v_cndmask_b32_e32 v218, v155, v218, vcc
	v_cmp_le_i32_e32 vcc, v166, v195
	s_nop 1
	v_cndmask_b32_e32 v235, v155, v235, vcc
	v_cmp_le_i32_e32 vcc, v167, v195
	s_nop 1
	v_cndmask_b32_e32 v220, v155, v220, vcc
	v_cmp_le_i32_e32 vcc, v168, v195
	s_nop 1
	v_cndmask_b32_e32 v236, v155, v236, vcc
	v_cmp_le_i32_e32 vcc, v169, v195
	s_nop 1
	v_cndmask_b32_e32 v221, v155, v221, vcc
	v_cmp_le_i32_e32 vcc, v170, v195
	s_nop 1
	v_cndmask_b32_e32 v237, v155, v237, vcc
	v_cmp_le_i32_e32 vcc, v171, v195
	s_nop 1
	v_cndmask_b32_e32 v222, v155, v222, vcc
	v_cmp_le_i32_e32 vcc, v172, v195
	s_nop 1
	v_cndmask_b32_e32 v238, v155, v238, vcc
	v_cmp_le_i32_e32 vcc, v173, v195
	s_nop 1
	v_cndmask_b32_e32 v223, v155, v223, vcc
	v_cmp_le_i32_e32 vcc, v174, v195
	s_nop 1
	v_cndmask_b32_e32 v239, v155, v239, vcc
	v_cmp_le_i32_e32 vcc, v175, v195
	s_nop 1
	v_cndmask_b32_e32 v224, v155, v224, vcc
	v_cmp_le_i32_e32 vcc, v176, v195
	s_nop 1
	v_cndmask_b32_e32 v240, v155, v240, vcc
	v_cmp_le_i32_e32 vcc, v177, v195
	s_nop 1
	v_cndmask_b32_e32 v225, v155, v225, vcc
	v_cmp_le_i32_e32 vcc, v178, v195
	s_nop 1
	v_cndmask_b32_e32 v241, v155, v241, vcc
	v_cmp_le_i32_e32 vcc, v179, v195
	s_nop 1
	v_cndmask_b32_e32 v226, v155, v226, vcc
	v_cmp_le_i32_e32 vcc, v180, v195
	s_nop 1
	v_cndmask_b32_e32 v242, v155, v242, vcc
	v_cmp_le_i32_e32 vcc, v181, v195
	s_nop 1
	v_cndmask_b32_e32 v227, v155, v227, vcc
	v_cmp_le_i32_e32 vcc, v182, v195
	s_nop 1
	v_cndmask_b32_e32 v243, v155, v243, vcc
	v_cmp_le_i32_e32 vcc, v183, v195
	s_nop 1
	v_cndmask_b32_e32 v228, v155, v228, vcc
	v_cmp_le_i32_e32 vcc, v184, v195
	s_nop 1
	v_cndmask_b32_e32 v244, v155, v244, vcc
	v_cmp_le_i32_e32 vcc, v185, v195
	s_nop 1
	v_cndmask_b32_e32 v229, v155, v229, vcc
	v_cmp_le_i32_e32 vcc, v186, v195
	s_nop 1
	v_cndmask_b32_e32 v245, v155, v245, vcc
	v_cmp_le_i32_e32 vcc, v187, v195
	s_nop 1
	v_cndmask_b32_e32 v230, v155, v230, vcc
	v_cmp_le_i32_e32 vcc, v188, v195
	s_nop 1
	v_cndmask_b32_e32 v246, v155, v246, vcc
	v_cmp_le_i32_e32 vcc, v189, v195
	s_nop 1
	v_cndmask_b32_e32 v231, v155, v231, vcc
	v_cmp_le_i32_e32 vcc, v190, v195
	s_nop 1
	v_cndmask_b32_e32 v247, v155, v247, vcc
	v_cmp_le_i32_e32 vcc, v191, v195
	s_nop 1
	v_cndmask_b32_e32 v232, v155, v232, vcc
	v_cmp_le_i32_e32 vcc, v192, v195
	s_nop 1
	v_cndmask_b32_e32 v248, v155, v248, vcc
	v_cmp_le_i32_e32 vcc, v193, v195
	s_nop 1
	v_cndmask_b32_e32 v233, v155, v233, vcc
	v_cmp_le_i32_e32 vcc, v194, v195
	s_nop 1
	v_cndmask_b32_e32 v249, v155, v249, vcc

.Lff1a_norsc:
	s_cmp_eq_u64 s[84:85], exec
	s_cselect_b32 s72, 0, 1
	s_cbranch_scc0 .Lff1a_bar
	s_lshl_b32 s86, s77, 2
	s_add_i32 s86, s86, 0x127fc
	v_mov_b32_e32 v252, s86
	ds_read_b32 v252, v252
	v_add_f32_e32 v253, 0xc3190000, v197
	s_waitcnt lgkmcnt(0)
	v_add_f32_e32 v252, v252, v151
	s_nop 0
	v_cmp_lt_f32_e32 vcc, v252, v253
	s_nop 1
	s_cmp_eq_u64 vcc, exec
	s_cbranch_scc0 .Lff1a_bar
	s_mov_b32 s74, 0x80000000
	s_branch .Lff1a_bar
.Lff1a_inact:
	s_cmp_lg_u32 s74, 0x80000000
	s_cbranch_scc1 .Lff1a_inact2
	s_lshr_b32 s86, s26, 6
	s_lshl_b32 s86, s86, 2
	s_add_i32 s86, s86, 0x1c100
	v_mov_b32_e32 v252, s86
	v_mov_b32_e32 v253, 1
	ds_add_u32 v252, v253

.Lff1a_bar:
	s_waitcnt lgkmcnt(0)
	s_barrier
	s_lshr_b32 s86, s26, 6
	s_lshl_b32 s86, s86, 2
	s_add_i32 s86, s86, 0x1c100
	v_mov_b32_e32 v252, s86
	ds_read_b32 v153, v252
	s_mov_b32 s71, s70
	s_mov_b32 s70, s69
	s_mov_b32 s69, s68
	s_mov_b32 s68, s71
	s_addk_i32 s4, 0x100
	s_add_i32 s26, s26, 64
	s_add_i32 s0, s0, 1
	s_cmp_lg_u32 s7, s4
	v_add_u32_e32 v195, 64, v195
	s_cbranch_scc0 .Lff1a_exit
	s_branch .Lff1b_top

.Lff1b_top:
	s_add_i32 s27, s0, -2
	s_and_b32 s27, s27, 1
	s_xor_b32 s34, s27, 1
	s_mul_i32 s35, s34, 0x4400
	s_add_i32 s35, s35, 0
	s_mulk_i32 s34, 0xc00
	s_add_i32 s34, s35, s34
	v_add3_u32 v0, s35, v157, v158
	s_waitcnt vmcnt(3)
	ds_write_b128 v0, v[130:133]
	v_add3_u32 v0, s68, v159, v158
	s_waitcnt vmcnt(2)
	ds_write_b128 v0, v[134:137] offset:34816
	v_add3_u32 v0, s35, v160, v161
	s_cmp_lt_u32 s0, s1
	s_waitcnt vmcnt(1)
	ds_write_b128 v0, v[138:141]
	v_add3_u32 v0, s68, v147, v161
	s_cselect_b32 s34, s0, s6
	s_sub_i32 s34, s6, s34
	s_lshl_b32 s34, s34, 20
	s_add_u32 s80, s78, s34
	s_addc_u32 s81, s79, 0
	s_add_u32 s80, s80, 0x1000
	s_addc_u32 s81, s81, 0
	s_add_u32 s82, s80, 0x1000
	s_addc_u32 s83, s81, 0
	s_waitcnt vmcnt(0)
	ds_write_b128 v0, v[142:145] offset:34816
	global_load_dwordx4 v[130:133], v150, s[80:81]
	global_load_dwordx4 v[134:137], v150, s[82:83]
	s_sub_i32 s34, s26, 63
	s_cmp_gt_i32 s34, s5
	global_load_dwordx4 v[138:141], v152, s[80:81]
	global_load_dwordx4 v[142:145], v152, s[82:83]
	s_lshr_b32 s77, s7, 2
	s_sub_i32 s77, s77, s26
	s_add_i32 s77, s77, -1
	s_sub_i32 s75, s7, s4
	s_add_i32 s75, s75, -256
	s_waitcnt lgkmcnt(4)
	v_readfirstlane_b32 s86, v153
	s_cmpk_eq_u32 s86, 0x200
	s_cbranch_scc1 .Lff1b_exit
	s_cmp_gt_i32 s77, s74
	s_cbranch_scc1 .Lff1b_inact
	s_cmp_eq_u32 s72, 0
	s_cbranch_scc1 .Lff1b_first
	s_mul_i32 s34, s27, 0x4400
	v_add_u32_e32 v0, s34, v162
	ds_read_b128 v[198:201], v0
	ds_read_b128 v[202:205], v0 offset:32
	ds_read_b128 v[206:209], v0 offset:8704
	ds_read_b128 v[210:213], v0 offset:8736
	v_add_u32_e32 v78, s75, v149
	v_add_u32_e32 v66, 0x12800, v78
	v_add_u32_e32 v67, 0x12880, v78
	v_add_u32_e32 v70, 0x12820, v78
	v_add_u32_e32 v71, 0x128a0, v78
	v_add_u32_e32 v74, 0x12840, v78
	v_add_u32_e32 v75, 0x128c0, v78
	v_add_u32_e32 v79, 0x12860, v78
	v_add_u32_e32 v78, 0x128e0, v78
	ds_read_b128 v[82:85], v66
	ds_read_b128 v[66:69], v67
	ds_read_b128 v[86:89], v70
	ds_read_b128 v[70:73], v71
	ds_read_b128 v[90:93], v74
	ds_read_b128 v[74:77], v75
	ds_read_b128 v[94:97], v79
	ds_read_b128 v[78:81], v78
	s_waitcnt lgkmcnt(1)
	v_mfma_f32_32x32x16_bf16 v[82:97], v[198:201], v[98:101], v[82:97]
	v_sub_f32_e32 v218, v218, v197
	v_sub_f32_e32 v219, v219, v197
	v_sub_f32_e32 v220, v220, v197
	v_sub_f32_e32 v221, v221, v197
	v_exp_f32_e32 v218, v218
	v_exp_f32_e32 v219, v219
	v_exp_f32_e32 v220, v220
	v_exp_f32_e32 v221, v221
	s_waitcnt lgkmcnt(0)
	v_mfma_f32_32x32x16_bf16 v[66:81], v[206:209], v[98:101], v[66:81]
	v_sub_f32_e32 v222, v222, v197
	v_sub_f32_e32 v223, v223, v197
	v_sub_f32_e32 v224, v224, v197
	v_sub_f32_e32 v225, v225, v197
	v_exp_f32_e32 v222, v222
	v_exp_f32_e32 v223, v223
	v_exp_f32_e32 v224, v224
	v_exp_f32_e32 v225, v225
	v_mfma_f32_32x32x16_bf16 v[82:97], v[202:205], v[102:105], v[82:97]
	v_sub_f32_e32 v234, v234, v197
	v_sub_f32_e32 v235, v235, v197
	v_sub_f32_e32 v236, v236, v197
	v_sub_f32_e32 v237, v237, v197
	v_exp_f32_e32 v234, v234
	v_exp_f32_e32 v235, v235
	v_exp_f32_e32 v236, v236
	v_exp_f32_e32 v237, v237
	ds_read_b128 v[198:201], v0 offset:64
	ds_read_b128 v[202:205], v0 offset:96
	ds_read_b128 v[206:209], v0 offset:8768
	ds_read_b128 v[214:217], v0 offset:8800
	v_mfma_f32_32x32x16_bf16 v[66:81], v[210:213], v[102:105], v[66:81]
	v_add_f32_e32 v250, v218, v222
	v_add_f32_e32 v251, v219, v223
	v_add_f32_e32 v252, v220, v224
	v_add_f32_e32 v253, v221, v225
	v_sub_f32_e32 v238, v238, v197
	v_sub_f32_e32 v239, v239, v197
	v_sub_f32_e32 v240, v240, v197
	v_sub_f32_e32 v241, v241, v197
	s_waitcnt lgkmcnt(3)
	v_mfma_f32_32x32x16_bf16 v[82:97], v[198:201], v[106:109], v[82:97]
	v_exp_f32_e32 v238, v238
	v_exp_f32_e32 v239, v239
	v_exp_f32_e32 v240, v240
	v_exp_f32_e32 v241, v241
	v_add_f32_e32 v250, v250, v234
	v_add_f32_e32 v251, v251, v235
	v_add_f32_e32 v252, v252, v236
	v_add_f32_e32 v253, v253, v237
	s_waitcnt lgkmcnt(1)
	v_mfma_f32_32x32x16_bf16 v[66:81], v[206:209], v[106:109], v[66:81]
	v_sub_f32_e32 v226, v226, v197
	v_sub_f32_e32 v227, v227, v197
	v_sub_f32_e32 v228, v228, v197
	v_sub_f32_e32 v229, v229, v197
	v_exp_f32_e32 v226, v226
	v_exp_f32_e32 v227, v227
	v_exp_f32_e32 v228, v228
	v_exp_f32_e32 v229, v229
	v_mfma_f32_32x32x16_bf16 v[82:97], v[202:205], v[110:113], v[82:97]
	v_add_f32_e32 v250, v250, v238
	v_add_f32_e32 v251, v251, v239
	v_add_f32_e32 v252, v252, v240
	v_add_f32_e32 v253, v253, v241
	v_sub_f32_e32 v230, v230, v197
	v_sub_f32_e32 v231, v231, v197
	v_sub_f32_e32 v232, v232, v197
	v_sub_f32_e32 v233, v233, v197
	ds_read_b128 v[198:201], v0 offset:128
	ds_read_b128 v[202:205], v0 offset:160
	ds_read_b128 v[206:209], v0 offset:8832
	ds_read_b128 v[210:213], v0 offset:8864
	s_waitcnt lgkmcnt(4)
	v_mfma_f32_32x32x16_bf16 v[66:81], v[214:217], v[110:113], v[66:81]
	v_exp_f32_e32 v230, v230
	v_exp_f32_e32 v231, v231
	v_exp_f32_e32 v232, v232
	v_exp_f32_e32 v233, v233
	v_add_f32_e32 v250, v250, v226
	v_add_f32_e32 v251, v251, v227
	v_add_f32_e32 v252, v252, v228
	v_add_f32_e32 v253, v253, v229
	s_waitcnt lgkmcnt(3)
	v_mfma_f32_32x32x16_bf16 v[82:97], v[198:201], v[114:117], v[82:97]
	v_sub_f32_e32 v242, v242, v197
	v_sub_f32_e32 v243, v243, v197
	v_sub_f32_e32 v244, v244, v197
	v_sub_f32_e32 v245, v245, v197
	v_exp_f32_e32 v242, v242
	v_exp_f32_e32 v243, v243
	v_exp_f32_e32 v244, v244
	v_exp_f32_e32 v245, v245
	s_waitcnt lgkmcnt(1)
	v_mfma_f32_32x32x16_bf16 v[66:81], v[206:209], v[114:117], v[66:81]
	v_add_f32_e32 v250, v250, v230
	v_add_f32_e32 v251, v251, v231
	v_add_f32_e32 v252, v252, v232
	v_add_f32_e32 v253, v253, v233
	v_sub_f32_e32 v246, v246, v197
	v_sub_f32_e32 v247, v247, v197
	v_sub_f32_e32 v248, v248, v197
	v_sub_f32_e32 v249, v249, v197
	v_mfma_f32_32x32x16_bf16 v[82:97], v[202:205], v[118:121], v[82:97]
	v_exp_f32_e32 v246, v246
	v_exp_f32_e32 v247, v247
	v_exp_f32_e32 v248, v248
	v_exp_f32_e32 v249, v249
	v_add_f32_e32 v250, v250, v242
	v_add_f32_e32 v251, v251, v243
	v_add_f32_e32 v252, v252, v244
	v_add_f32_e32 v253, v253, v245
	ds_read_b128 v[198:201], v0 offset:192
	ds_read_b128 v[202:205], v0 offset:224
	ds_read_b128 v[206:209], v0 offset:8896
	ds_read_b128 v[214:217], v0 offset:8928
	s_waitcnt lgkmcnt(4)
	v_mfma_f32_32x32x16_bf16 v[66:81], v[210:213], v[118:121], v[66:81]
	v_add_f32_e32 v250, v250, v246
	v_add_f32_e32 v251, v251, v247
	v_add_f32_e32 v252, v252, v248
	v_add_f32_e32 v253, v253, v249
	v_add_f32_e32 v250, v250, v251
	v_add_f32_e32 v252, v252, v253
	v_add_f32_e32 v250, v250, v252
	v_add_f32_e32 v196, v196, v250
	s_waitcnt lgkmcnt(3)
	v_mfma_f32_32x32x16_bf16 v[82:97], v[198:201], v[122:125], v[82:97]
	v_cvt_pk_bf16_f32 v241, v240, v241
	v_cvt_pk_bf16_f32 v240, v238, v239
	v_cvt_pk_bf16_f32 v239, v236, v237
	v_cvt_pk_bf16_f32 v238, v234, v235
	v_cvt_pk_bf16_f32 v234, v218, v219
	v_cvt_pk_bf16_f32 v235, v220, v221
	v_cvt_pk_bf16_f32 v236, v222, v223
	v_cvt_pk_bf16_f32 v237, v224, v225
	s_waitcnt lgkmcnt(1)
	v_mfma_f32_32x32x16_bf16 v[66:81], v[206:209], v[122:125], v[66:81]
	v_cvt_pk_bf16_f32 v249, v248, v249
	v_cvt_pk_bf16_f32 v248, v246, v247
	v_cvt_pk_bf16_f32 v247, v244, v245
	v_cvt_pk_bf16_f32 v246, v242, v243
	v_cvt_pk_bf16_f32 v242, v226, v227
	v_cvt_pk_bf16_f32 v243, v228, v229
	v_cvt_pk_bf16_f32 v244, v230, v231
	v_cvt_pk_bf16_f32 v245, v232, v233
	v_mfma_f32_32x32x16_bf16 v[82:97], v[202:205], v[126:129], v[82:97]
	s_waitcnt lgkmcnt(0)
	v_mfma_f32_32x32x16_bf16 v[66:81], v[214:217], v[126:129], v[66:81]
	s_add_i32 s76, s77, 63
	s_cmp_le_i32 s76, s5
	s_cbranch_scc1 .Lff1b_z2
	v_cmp_le_i32_e32 vcc, v165, v195
	s_nop 8
	v_cndmask_b32_e32 v66, v155, v66, vcc
	v_cmp_lt_i32_e32 vcc, v163, v195
	s_nop 1
	v_cndmask_b32_e32 v83, v155, v83, vcc
	v_cmp_le_i32_e32 vcc, v163, v195
	s_nop 1
	v_cndmask_b32_e32 v82, v155, v82, vcc
	v_cmp_le_i32_e32 vcc, v166, v195
	s_nop 1
	v_cndmask_b32_e32 v67, v155, v67, vcc
	v_cmp_le_i32_e32 vcc, v167, v195
	s_nop 1
	v_cndmask_b32_e32 v84, v155, v84, vcc
	v_cmp_le_i32_e32 vcc, v168, v195
	s_nop 1
	v_cndmask_b32_e32 v68, v155, v68, vcc
	v_cmp_le_i32_e32 vcc, v169, v195
	s_nop 1
	v_cndmask_b32_e32 v85, v155, v85, vcc
	v_cmp_le_i32_e32 vcc, v170, v195
	s_nop 1
	v_cndmask_b32_e32 v69, v155, v69, vcc
	v_cmp_le_i32_e32 vcc, v171, v195
	s_nop 1
	v_cndmask_b32_e32 v86, v155, v86, vcc
	v_cmp_le_i32_e32 vcc, v172, v195
	s_nop 1
	v_cndmask_b32_e32 v70, v155, v70, vcc
	v_cmp_le_i32_e32 vcc, v173, v195
	s_nop 1
	v_cndmask_b32_e32 v87, v155, v87, vcc
	v_cmp_le_i32_e32 vcc, v174, v195
	s_nop 1
	v_cndmask_b32_e32 v71, v155, v71, vcc
	v_cmp_le_i32_e32 vcc, v175, v195
	s_nop 1
	v_cndmask_b32_e32 v88, v155, v88, vcc
	v_cmp_le_i32_e32 vcc, v176, v195
	s_nop 1
	v_cndmask_b32_e32 v72, v155, v72, vcc
	v_cmp_le_i32_e32 vcc, v177, v195
	s_nop 1
	v_cndmask_b32_e32 v89, v155, v89, vcc
	v_cmp_le_i32_e32 vcc, v178, v195
	s_nop 1
	v_cndmask_b32_e32 v73, v155, v73, vcc
	v_cmp_le_i32_e32 vcc, v179, v195
	s_nop 1
	v_cndmask_b32_e32 v90, v155, v90, vcc
	v_cmp_le_i32_e32 vcc, v180, v195
	s_nop 1
	v_cndmask_b32_e32 v74, v155, v74, vcc
	v_cmp_le_i32_e32 vcc, v181, v195
	s_nop 1
	v_cndmask_b32_e32 v91, v155, v91, vcc
	v_cmp_le_i32_e32 vcc, v182, v195
	s_nop 1
	v_cndmask_b32_e32 v75, v155, v75, vcc
	v_cmp_le_i32_e32 vcc, v183, v195
	s_nop 1
	v_cndmask_b32_e32 v92, v155, v92, vcc
	v_cmp_le_i32_e32 vcc, v184, v195
	s_nop 1
	v_cndmask_b32_e32 v76, v155, v76, vcc
	v_cmp_le_i32_e32 vcc, v185, v195
	s_nop 1
	v_cndmask_b32_e32 v93, v155, v93, vcc
	v_cmp_le_i32_e32 vcc, v186, v195
	s_nop 1
	v_cndmask_b32_e32 v77, v155, v77, vcc
	v_cmp_le_i32_e32 vcc, v187, v195
	s_nop 1
	v_cndmask_b32_e32 v94, v155, v94, vcc
	v_cmp_le_i32_e32 vcc, v188, v195
	s_nop 1
	v_cndmask_b32_e32 v78, v155, v78, vcc
	v_cmp_le_i32_e32 vcc, v189, v195
	s_nop 1
	v_cndmask_b32_e32 v95, v155, v95, vcc
	v_cmp_le_i32_e32 vcc, v190, v195
	s_nop 1
	v_cndmask_b32_e32 v79, v155, v79, vcc
	v_cmp_le_i32_e32 vcc, v191, v195
	s_nop 1
	v_cndmask_b32_e32 v96, v155, v96, vcc
	v_cmp_le_i32_e32 vcc, v192, v195
	s_nop 1
	v_cndmask_b32_e32 v80, v155, v80, vcc
	v_cmp_le_i32_e32 vcc, v193, v195
	s_nop 1
	v_cndmask_b32_e32 v97, v155, v97, vcc
	v_cmp_le_i32_e32 vcc, v194, v195
	s_nop 1
	v_cndmask_b32_e32 v81, v155, v81, vcc
